# speedup vs baseline: 1.0216x; 1.0176x over previous
; #define WAIT_L(n) asm volatile("s_waitcnt lgkmcnt(" #n ")" ::: "memory")
; #define BAR __builtin_amdgcn_s_barrier()
; #define SCHED __builtin_amdgcn_sched_barrier(0)
;     ...
;   for (int t = 0; t < nt - 2; t += 2) {
;     LDB(B0, 0, 0); SCHED; LDA(At, 0, 0); STAGE(SA(1, 1), A, brow + HALF, t + 1);
;     WAIT_L(8); BAR; WAIT_L(0); MMA(0, 0, At, B0); BAR; SCHED;
;     LDB(B1, 0, 1); STAGE(SB(0, 0), Bt, bcol, t + 2);
;     BAR; WAIT_L(0); MMA(0, 1, At, B1); BAR;
;     LDA(At, 0, 1); STAGE(SA(0, 0), A, brow, t + 2);
;     BAR; WAIT_L(0); MMA(1, 0, At, B0); BAR; SCHED;
.LBB0_69:
	ds_read_b128 v[166:169], v162
	ds_read_b128 v[170:173], v162 offset:1024
	ds_read_b128 v[174:177], v162 offset:2048
	ds_read_b128 v[178:181], v162 offset:3072
	v_add_u32_e32 v163, 0xc000, v147
	v_lshl_add_u64 v[182:183], v[134:135], 0, s[8:9]
	v_readfirstlane_b32 s11, v163
	v_lshl_add_u64 v[164:165], v[182:183], 0, s[26:27]
	s_mov_b32 m0, s11
	ds_read_b128 v[186:189], v144
	ds_read_b128 v[190:193], v144 offset:1024
	ds_read_b128 v[194:197], v141
	ds_read_b128 v[198:201], v141 offset:1024
	ds_read_b128 v[202:205], v140
	ds_read_b128 v[206:209], v140 offset:1024
	ds_read_b128 v[210:213], v139
	ds_read_b128 v[214:217], v139 offset:1024
	global_load_lds_dwordx4 v[164:165], off
	v_add_u32_e32 v164, 0xe000, v147
	v_lshl_add_u64 v[230:231], v[136:137], 0, s[8:9]
	v_readfirstlane_b32 s11, v164
	v_lshl_add_u64 v[218:219], v[230:231], 0, s[26:27]
	s_mov_b32 m0, s11
	s_nop 0
	global_load_lds_dwordx4 v[218:219], off
	s_waitcnt lgkmcnt(8)
	s_barrier
	s_waitcnt lgkmcnt(0)
	s_waitcnt lgkmcnt(0)
	v_mfma_f32_16x16x32_bf16 v[124:127], v[166:169], v[186:189], v[124:127]
	v_mfma_f32_16x16x32_bf16 v[120:123], v[174:177], v[186:189], v[120:123]
	v_mfma_f32_16x16x32_bf16 v[116:119], v[166:169], v[194:197], v[116:119]
	v_mfma_f32_16x16x32_bf16 v[112:115], v[174:177], v[194:197], v[112:115]
	v_mfma_f32_16x16x32_bf16 v[108:111], v[166:169], v[202:205], v[108:111]
	v_mfma_f32_16x16x32_bf16 v[104:107], v[174:177], v[202:205], v[104:107]
	v_mfma_f32_16x16x32_bf16 v[100:103], v[166:169], v[210:213], v[100:103]
	v_mfma_f32_16x16x32_bf16 v[96:99], v[174:177], v[210:213], v[96:99]
	v_mfma_f32_16x16x32_bf16 v[124:127], v[170:173], v[190:193], v[124:127]
	v_mfma_f32_16x16x32_bf16 v[120:123], v[178:181], v[190:193], v[120:123]
	v_mfma_f32_16x16x32_bf16 v[116:119], v[170:173], v[198:201], v[116:119]
	v_mfma_f32_16x16x32_bf16 v[112:115], v[178:181], v[198:201], v[112:115]
	v_mfma_f32_16x16x32_bf16 v[108:111], v[170:173], v[206:209], v[108:111]
	v_mfma_f32_16x16x32_bf16 v[104:107], v[178:181], v[206:209], v[104:107]
	v_mfma_f32_16x16x32_bf16 v[100:103], v[170:173], v[214:217], v[100:103]
	v_mfma_f32_16x16x32_bf16 v[96:99], v[178:181], v[214:217], v[96:99]
	s_barrier
	v_lshl_add_u64 v[244:245], v[130:131], 0, s[8:9]
	v_readfirstlane_b32 s11, v145
	v_lshl_add_u64 v[246:247], v[244:245], 0, s[28:29]
	s_mov_b32 m0, s11
	ds_read_b128 v[218:221], v161
	ds_read_b128 v[222:225], v161 offset:1024
	ds_read_b128 v[226:229], v161 offset:2048
	ds_read_b128 v[240:243], v161 offset:3072
	global_load_lds_dwordx4 v[246:247], off
	v_lshl_add_u64 v[246:247], v[132:133], 0, s[8:9]
	v_readfirstlane_b32 s11, v146
	v_lshl_add_u64 v[248:249], v[246:247], 0, s[28:29]
	s_mov_b32 m0, s11
	s_nop 0
	global_load_lds_dwordx4 v[248:249], off
	s_barrier
	s_waitcnt lgkmcnt(0)
	s_waitcnt lgkmcnt(0)
	v_mfma_f32_16x16x32_bf16 v[92:95], v[218:221], v[186:189], v[92:95]
	v_mfma_f32_16x16x32_bf16 v[88:91], v[226:229], v[186:189], v[88:91]
	v_mfma_f32_16x16x32_bf16 v[84:87], v[218:221], v[194:197], v[84:87]
	v_mfma_f32_16x16x32_bf16 v[80:83], v[226:229], v[194:197], v[80:83]
	v_mfma_f32_16x16x32_bf16 v[76:79], v[218:221], v[202:205], v[76:79]
	v_mfma_f32_16x16x32_bf16 v[72:75], v[226:229], v[202:205], v[72:75]
	v_mfma_f32_16x16x32_bf16 v[68:71], v[218:221], v[210:213], v[68:71]
	v_mfma_f32_16x16x32_bf16 v[64:67], v[226:229], v[210:213], v[64:67]
	v_mfma_f32_16x16x32_bf16 v[92:95], v[222:225], v[190:193], v[92:95]
	v_mfma_f32_16x16x32_bf16 v[88:91], v[240:243], v[190:193], v[88:91]
	v_mfma_f32_16x16x32_bf16 v[84:87], v[222:225], v[198:201], v[84:87]
	v_mfma_f32_16x16x32_bf16 v[80:83], v[240:243], v[198:201], v[80:83]
	v_mfma_f32_16x16x32_bf16 v[76:79], v[222:225], v[206:209], v[76:79]
	v_mfma_f32_16x16x32_bf16 v[72:75], v[240:243], v[206:209], v[72:75]
	v_mfma_f32_16x16x32_bf16 v[68:71], v[222:225], v[214:217], v[68:71]
	v_mfma_f32_16x16x32_bf16 v[64:67], v[240:243], v[214:217], v[64:67]
	v_readfirstlane_b32 s11, v147
	v_lshl_add_u64 v[248:249], v[182:183], 0, s[28:29]
	s_mov_b32 m0, s11
	v_readfirstlane_b32 s11, v149
	s_barrier
	ds_read_b128 v[186:189], v144 offset:16384
	ds_read_b128 v[190:193], v144 offset:17408
	ds_read_b128 v[194:197], v141 offset:16384
	ds_read_b128 v[198:201], v141 offset:17408
	ds_read_b128 v[202:205], v140 offset:16384
	ds_read_b128 v[206:209], v140 offset:17408
	ds_read_b128 v[210:213], v139 offset:16384
	ds_read_b128 v[214:217], v139 offset:17408
	global_load_lds_dwordx4 v[248:249], off
	v_lshl_add_u64 v[248:249], v[230:231], 0, s[28:29]
	s_mov_b32 m0, s11
	s_nop 0
	global_load_lds_dwordx4 v[248:249], off
	s_barrier
	s_waitcnt lgkmcnt(0)
	s_waitcnt lgkmcnt(0)
	v_mfma_f32_16x16x32_bf16 v[60:63], v[166:169], v[186:189], v[60:63]
	v_mfma_f32_16x16x32_bf16 v[56:59], v[174:177], v[186:189], v[56:59]
	v_mfma_f32_16x16x32_bf16 v[52:55], v[166:169], v[194:197], v[52:55]
	v_mfma_f32_16x16x32_bf16 v[48:51], v[174:177], v[194:197], v[48:51]
	v_mfma_f32_16x16x32_bf16 v[44:47], v[166:169], v[202:205], v[44:47]
	v_mfma_f32_16x16x32_bf16 v[40:43], v[174:177], v[202:205], v[40:43]
	v_mfma_f32_16x16x32_bf16 v[36:39], v[166:169], v[210:213], v[36:39]
	v_mfma_f32_16x16x32_bf16 v[32:35], v[174:177], v[210:213], v[32:35]
	v_mfma_f32_16x16x32_bf16 v[60:63], v[170:173], v[190:193], v[60:63]
	v_mfma_f32_16x16x32_bf16 v[56:59], v[178:181], v[190:193], v[56:59]
	v_mfma_f32_16x16x32_bf16 v[52:55], v[170:173], v[198:201], v[52:55]
	v_mfma_f32_16x16x32_bf16 v[48:51], v[178:181], v[198:201], v[48:51]
	v_mfma_f32_16x16x32_bf16 v[44:47], v[170:173], v[206:209], v[44:47]
	v_mfma_f32_16x16x32_bf16 v[40:43], v[178:181], v[206:209], v[40:43]
	v_mfma_f32_16x16x32_bf16 v[36:39], v[170:173], v[214:217], v[36:39]
	v_mfma_f32_16x16x32_bf16 v[32:35], v[178:181], v[214:217], v[32:35]
	s_barrier
; #define WAIT_V(n) asm volatile("s_waitcnt vmcnt(" #n ")" ::: "memory")
; #define WAIT_L(n) asm volatile("s_waitcnt lgkmcnt(" #n ")" ::: "memory")
; #define BAR __builtin_amdgcn_s_barrier()
; #define SCHED __builtin_amdgcn_sched_barrier(0)
;     ...
;     STAGE(SB(0, 1), Bt, bcol1, t + 2);
;     WAIT_V(6); BAR; MMA(1, 1, At, B1); BAR;
;     LDB(B0, 1, 0); SCHED; LDA(At, 1, 0); STAGE(SA(0, 1), A, brow + HALF, t + 2);
;     WAIT_L(8); BAR; WAIT_L(0); MMA(0, 0, At, B0); BAR; SCHED;
;     LDB(B1, 1, 1); STAGE(SB(1, 0), Bt, bcol, t + 3);
;     BAR; WAIT_L(0); MMA(0, 1, At, B1); BAR;
;     LDA(At, 1, 1); STAGE(SA(1, 0), A, brow, t + 3);
	v_readfirstlane_b32 s11, v150
	v_lshl_add_u64 v[166:167], v[244:245], 0, s[30:31]
	s_mov_b32 m0, s11
	v_readfirstlane_b32 s11, v151
	global_load_lds_dwordx4 v[166:167], off
	v_lshl_add_u64 v[166:167], v[246:247], 0, s[30:31]
	s_mov_b32 m0, s11
	s_nop 0
	global_load_lds_dwordx4 v[166:167], off
	s_waitcnt vmcnt(6)
	s_barrier
	v_mfma_f32_16x16x32_bf16 v[28:31], v[218:221], v[186:189], v[28:31]
	v_mfma_f32_16x16x32_bf16 v[24:27], v[226:229], v[186:189], v[24:27]
	v_mfma_f32_16x16x32_bf16 v[20:23], v[218:221], v[194:197], v[20:23]
	v_mfma_f32_16x16x32_bf16 v[16:19], v[226:229], v[194:197], v[16:19]
	v_mfma_f32_16x16x32_bf16 v[12:15], v[218:221], v[202:205], v[12:15]
	v_mfma_f32_16x16x32_bf16 v[8:11], v[226:229], v[202:205], v[8:11]
	v_mfma_f32_16x16x32_bf16 v[4:7], v[218:221], v[210:213], v[4:7]
	v_mfma_f32_16x16x32_bf16 v[0:3], v[226:229], v[210:213], v[0:3]
	v_mfma_f32_16x16x32_bf16 v[28:31], v[222:225], v[190:193], v[28:31]
	v_mfma_f32_16x16x32_bf16 v[24:27], v[240:243], v[190:193], v[24:27]
	v_mfma_f32_16x16x32_bf16 v[20:23], v[222:225], v[198:201], v[20:23]
	v_mfma_f32_16x16x32_bf16 v[16:19], v[240:243], v[198:201], v[16:19]
	v_mfma_f32_16x16x32_bf16 v[12:15], v[222:225], v[206:209], v[12:15]
	v_mfma_f32_16x16x32_bf16 v[8:11], v[240:243], v[206:209], v[8:11]
	v_mfma_f32_16x16x32_bf16 v[4:7], v[222:225], v[214:217], v[4:7]
	v_mfma_f32_16x16x32_bf16 v[0:3], v[240:243], v[214:217], v[0:3]
	s_barrier
	ds_read_b128 v[166:169], v152
	ds_read_b128 v[170:173], v152 offset:1024
	ds_read_b128 v[174:177], v152 offset:2048
	ds_read_b128 v[178:181], v152 offset:3072
	v_readfirstlane_b32 s11, v153
	v_lshl_add_u64 v[218:219], v[182:183], 0, s[30:31]
	s_mov_b32 m0, s11
	v_readfirstlane_b32 s11, v154
	ds_read_b128 v[186:189], v144 offset:32768
	ds_read_b128 v[190:193], v144 offset:33792
	ds_read_b128 v[194:197], v141 offset:32768
	ds_read_b128 v[198:201], v141 offset:33792
	ds_read_b128 v[202:205], v140 offset:32768
	ds_read_b128 v[206:209], v140 offset:33792
	ds_read_b128 v[210:213], v139 offset:32768
	ds_read_b128 v[214:217], v139 offset:33792
	global_load_lds_dwordx4 v[218:219], off
	v_lshl_add_u64 v[218:219], v[230:231], 0, s[30:31]
	s_mov_b32 m0, s11
	s_nop 0
	global_load_lds_dwordx4 v[218:219], off
	s_waitcnt lgkmcnt(8)
	s_barrier
	s_waitcnt lgkmcnt(0)
	s_waitcnt lgkmcnt(0)
	v_mfma_f32_16x16x32_bf16 v[124:127], v[166:169], v[186:189], v[124:127]
	v_mfma_f32_16x16x32_bf16 v[120:123], v[174:177], v[186:189], v[120:123]
	v_mfma_f32_16x16x32_bf16 v[116:119], v[166:169], v[194:197], v[116:119]
	v_mfma_f32_16x16x32_bf16 v[112:115], v[174:177], v[194:197], v[112:115]
	v_mfma_f32_16x16x32_bf16 v[108:111], v[166:169], v[202:205], v[108:111]
	v_mfma_f32_16x16x32_bf16 v[104:107], v[174:177], v[202:205], v[104:107]
	v_mfma_f32_16x16x32_bf16 v[100:103], v[166:169], v[210:213], v[100:103]
	v_mfma_f32_16x16x32_bf16 v[96:99], v[174:177], v[210:213], v[96:99]
	v_mfma_f32_16x16x32_bf16 v[124:127], v[170:173], v[190:193], v[124:127]
	v_mfma_f32_16x16x32_bf16 v[120:123], v[178:181], v[190:193], v[120:123]
	v_mfma_f32_16x16x32_bf16 v[116:119], v[170:173], v[198:201], v[116:119]
	v_mfma_f32_16x16x32_bf16 v[112:115], v[178:181], v[198:201], v[112:115]
	v_mfma_f32_16x16x32_bf16 v[108:111], v[170:173], v[206:209], v[108:111]
	v_mfma_f32_16x16x32_bf16 v[104:107], v[178:181], v[206:209], v[104:107]
	v_mfma_f32_16x16x32_bf16 v[100:103], v[170:173], v[214:217], v[100:103]
	v_mfma_f32_16x16x32_bf16 v[96:99], v[178:181], v[214:217], v[96:99]
	s_barrier
	v_readfirstlane_b32 s11, v155
	v_lshl_add_u64 v[248:249], v[244:245], 0, s[34:35]
	s_mov_b32 m0, s11
	v_readfirstlane_b32 s11, v156
	ds_read_b128 v[218:221], v148
	ds_read_b128 v[222:225], v148 offset:1024
	ds_read_b128 v[226:229], v148 offset:2048
	ds_read_b128 v[240:243], v148 offset:3072
	global_load_lds_dwordx4 v[248:249], off
	v_lshl_add_u64 v[248:249], v[246:247], 0, s[34:35]
	s_mov_b32 m0, s11
	s_nop 0
	global_load_lds_dwordx4 v[248:249], off
	s_barrier
	s_waitcnt lgkmcnt(0)
	s_waitcnt lgkmcnt(0)
	v_mfma_f32_16x16x32_bf16 v[92:95], v[218:221], v[186:189], v[92:95]
	v_mfma_f32_16x16x32_bf16 v[88:91], v[226:229], v[186:189], v[88:91]
	v_mfma_f32_16x16x32_bf16 v[84:87], v[218:221], v[194:197], v[84:87]
	v_mfma_f32_16x16x32_bf16 v[80:83], v[226:229], v[194:197], v[80:83]
	v_mfma_f32_16x16x32_bf16 v[76:79], v[218:221], v[202:205], v[76:79]
	v_mfma_f32_16x16x32_bf16 v[72:75], v[226:229], v[202:205], v[72:75]
	v_mfma_f32_16x16x32_bf16 v[68:71], v[218:221], v[210:213], v[68:71]
	v_mfma_f32_16x16x32_bf16 v[64:67], v[226:229], v[210:213], v[64:67]
	v_mfma_f32_16x16x32_bf16 v[92:95], v[222:225], v[190:193], v[92:95]
	v_mfma_f32_16x16x32_bf16 v[88:91], v[240:243], v[190:193], v[88:91]
	v_mfma_f32_16x16x32_bf16 v[84:87], v[222:225], v[198:201], v[84:87]
	v_mfma_f32_16x16x32_bf16 v[80:83], v[240:243], v[198:201], v[80:83]
	v_mfma_f32_16x16x32_bf16 v[76:79], v[222:225], v[206:209], v[76:79]
	v_mfma_f32_16x16x32_bf16 v[72:75], v[240:243], v[206:209], v[72:75]
	v_mfma_f32_16x16x32_bf16 v[68:71], v[222:225], v[214:217], v[68:71]
	v_mfma_f32_16x16x32_bf16 v[64:67], v[240:243], v[214:217], v[64:67]
	v_readfirstlane_b32 s11, v157
	v_lshl_add_u64 v[182:183], v[182:183], 0, s[34:35]
	s_mov_b32 m0, s11
	v_readfirstlane_b32 s11, v158
	s_barrier
	ds_read_b128 v[186:189], v144 offset:49152
	ds_read_b128 v[190:193], v144 offset:50176
	ds_read_b128 v[194:197], v141 offset:49152
	ds_read_b128 v[198:201], v141 offset:50176
	ds_read_b128 v[202:205], v140 offset:49152
	ds_read_b128 v[206:209], v140 offset:50176
	ds_read_b128 v[210:213], v139 offset:49152
	ds_read_b128 v[214:217], v139 offset:50176
	global_load_lds_dwordx4 v[182:183], off
	v_lshl_add_u64 v[182:183], v[230:231], 0, s[34:35]
	s_mov_b32 m0, s11
	s_nop 0
	global_load_lds_dwordx4 v[182:183], off
	s_barrier
; #define WAIT_V(n) asm volatile("s_waitcnt vmcnt(" #n ")" ::: "memory")
; #define WAIT_L(n) asm volatile("s_waitcnt lgkmcnt(" #n ")" ::: "memory")
; #define BAR __builtin_amdgcn_s_barrier()
; #define SCHED __builtin_amdgcn_sched_barrier(0)
;     ...
;     BAR; WAIT_L(0); MMA(1, 0, At, B0); BAR; SCHED;
;     STAGE(SB(1, 1), Bt, bcol1, t + 3);
;     WAIT_V(6); BAR; MMA(1, 1, At, B1); BAR;
;   }
;   { LDB(B0, 0, 0); LDA(At, 0, 0); STAGE(SA(1, 1), A, brow + HALF, nt - 1);
;     BAR; WAIT_L(0); MMA(0, 0, At, B0); BAR;
;     LDB(B1, 0, 1); BAR; WAIT_L(0); MMA(0, 1, At, B1); BAR;
	s_waitcnt lgkmcnt(0)
	s_waitcnt lgkmcnt(0)
	v_mfma_f32_16x16x32_bf16 v[60:63], v[166:169], v[186:189], v[60:63]
	v_mfma_f32_16x16x32_bf16 v[56:59], v[174:177], v[186:189], v[56:59]
	v_mfma_f32_16x16x32_bf16 v[52:55], v[166:169], v[194:197], v[52:55]
	v_mfma_f32_16x16x32_bf16 v[48:51], v[174:177], v[194:197], v[48:51]
	v_mfma_f32_16x16x32_bf16 v[44:47], v[166:169], v[202:205], v[44:47]
	v_mfma_f32_16x16x32_bf16 v[40:43], v[174:177], v[202:205], v[40:43]
	v_mfma_f32_16x16x32_bf16 v[36:39], v[166:169], v[210:213], v[36:39]
	v_mfma_f32_16x16x32_bf16 v[32:35], v[174:177], v[210:213], v[32:35]
	v_mfma_f32_16x16x32_bf16 v[60:63], v[170:173], v[190:193], v[60:63]
	v_mfma_f32_16x16x32_bf16 v[56:59], v[178:181], v[190:193], v[56:59]
	v_mfma_f32_16x16x32_bf16 v[52:55], v[170:173], v[198:201], v[52:55]
	v_mfma_f32_16x16x32_bf16 v[48:51], v[178:181], v[198:201], v[48:51]
	v_mfma_f32_16x16x32_bf16 v[44:47], v[170:173], v[206:209], v[44:47]
	v_mfma_f32_16x16x32_bf16 v[40:43], v[178:181], v[206:209], v[40:43]
	v_mfma_f32_16x16x32_bf16 v[36:39], v[170:173], v[214:217], v[36:39]
	v_mfma_f32_16x16x32_bf16 v[32:35], v[178:181], v[214:217], v[32:35]
	s_barrier
	v_readfirstlane_b32 s11, v159
	v_lshl_add_u64 v[166:167], v[244:245], 0, s[36:37]
	s_mov_b32 m0, s11
	v_readfirstlane_b32 s11, v160
	global_load_lds_dwordx4 v[166:167], off
	v_lshl_add_u64 v[166:167], v[246:247], 0, s[36:37]
	s_mov_b32 m0, s11
	s_nop 0
	global_load_lds_dwordx4 v[166:167], off
	s_waitcnt vmcnt(6)
	s_barrier
	v_mfma_f32_16x16x32_bf16 v[28:31], v[218:221], v[186:189], v[28:31]
	v_mfma_f32_16x16x32_bf16 v[24:27], v[226:229], v[186:189], v[24:27]
	v_mfma_f32_16x16x32_bf16 v[20:23], v[218:221], v[194:197], v[20:23]
	v_mfma_f32_16x16x32_bf16 v[16:19], v[226:229], v[194:197], v[16:19]
	v_mfma_f32_16x16x32_bf16 v[12:15], v[218:221], v[202:205], v[12:15]
	v_mfma_f32_16x16x32_bf16 v[8:11], v[226:229], v[202:205], v[8:11]
	v_mfma_f32_16x16x32_bf16 v[4:7], v[218:221], v[210:213], v[4:7]
	v_mfma_f32_16x16x32_bf16 v[0:3], v[226:229], v[210:213], v[0:3]
	v_mfma_f32_16x16x32_bf16 v[28:31], v[222:225], v[190:193], v[28:31]
	v_mfma_f32_16x16x32_bf16 v[24:27], v[240:243], v[190:193], v[24:27]
	v_mfma_f32_16x16x32_bf16 v[20:23], v[222:225], v[198:201], v[20:23]
	v_mfma_f32_16x16x32_bf16 v[16:19], v[240:243], v[198:201], v[16:19]
	v_mfma_f32_16x16x32_bf16 v[12:15], v[222:225], v[206:209], v[12:15]
	v_mfma_f32_16x16x32_bf16 v[8:11], v[240:243], v[206:209], v[8:11]
	v_mfma_f32_16x16x32_bf16 v[4:7], v[222:225], v[214:217], v[4:7]
	v_mfma_f32_16x16x32_bf16 v[0:3], v[240:243], v[214:217], v[0:3]
	s_add_i32 s10, s10, 2
	s_add_u32 s8, s8, 0x100
	s_addc_u32 s9, s9, 0
	s_cmp_lt_u32 s10, 60
	s_barrier
	s_cbranch_scc1 .LBB0_69
	s_add_u32 s4, s4, 0x1f80
	s_addc_u32 s5, s5, 0
	v_readfirstlane_b32 s8, v163
	v_lshl_add_u64 v[146:147], s[4:5], 0, v[184:185]
	s_mov_b32 m0, s8
	v_lshl_add_u64 v[128:129], s[4:5], 0, v[128:129]
	v_readfirstlane_b32 s4, v164
	ds_read_b128 v[130:133], v162
	ds_read_b128 v[134:137], v162 offset:1024
	ds_read_b128 v[154:157], v162 offset:2048
	ds_read_b128 v[166:169], v162 offset:3072
	ds_read_b128 v[170:173], v144
	ds_read_b128 v[174:177], v144 offset:1024
	ds_read_b128 v[178:181], v141
	ds_read_b128 v[186:189], v141 offset:1024
	ds_read_b128 v[190:193], v140
	ds_read_b128 v[194:197], v140 offset:1024
	ds_read_b128 v[198:201], v139
	ds_read_b128 v[202:205], v139 offset:1024
	global_load_lds_dwordx4 v[146:147], off
	s_mov_b32 m0, s4
	s_nop 0
	global_load_lds_dwordx4 v[128:129], off
	s_barrier
	s_waitcnt lgkmcnt(0)
	s_waitcnt lgkmcnt(0)
	v_mfma_f32_16x16x32_bf16 v[124:127], v[130:133], v[170:173], v[124:127]
	v_mfma_f32_16x16x32_bf16 v[120:123], v[154:157], v[170:173], v[120:123]
	v_mfma_f32_16x16x32_bf16 v[116:119], v[130:133], v[178:181], v[116:119]
	v_mfma_f32_16x16x32_bf16 v[108:111], v[130:133], v[190:193], v[108:111]
	v_mfma_f32_16x16x32_bf16 v[104:107], v[154:157], v[190:193], v[104:107]
	v_mfma_f32_16x16x32_bf16 v[124:127], v[134:137], v[174:177], v[124:127]
	v_mfma_f32_16x16x32_bf16 v[120:123], v[166:169], v[174:177], v[120:123]
	v_mfma_f32_16x16x32_bf16 v[116:119], v[134:137], v[186:189], v[116:119]
	v_mfma_f32_16x16x32_bf16 v[112:115], v[154:157], v[178:181], v[112:115]
	v_mfma_f32_16x16x32_bf16 v[108:111], v[134:137], v[194:197], v[108:111]
	v_mfma_f32_16x16x32_bf16 v[104:107], v[166:169], v[194:197], v[104:107]
	v_mfma_f32_16x16x32_bf16 v[100:103], v[130:133], v[198:201], v[100:103]
	v_mfma_f32_16x16x32_bf16 v[96:99], v[154:157], v[198:201], v[96:99]
	v_mfma_f32_16x16x32_bf16 v[162:165], v[166:169], v[186:189], v[112:115]
	v_mfma_f32_16x16x32_bf16 v[206:209], v[134:137], v[202:205], v[100:103]
	v_mfma_f32_16x16x32_bf16 v[210:213], v[166:169], v[202:205], v[96:99]
	s_barrier
	s_nop 2
	ds_read_b128 v[96:99], v161
	ds_read_b128 v[100:103], v161 offset:1024
	ds_read_b128 v[112:115], v161 offset:2048
	ds_read_b128 v[158:161], v161 offset:3072
	s_barrier
	s_waitcnt lgkmcnt(0)
	s_waitcnt lgkmcnt(0)
	v_mfma_f32_16x16x32_bf16 v[92:95], v[96:99], v[170:173], v[92:95]
	v_mfma_f32_16x16x32_bf16 v[88:91], v[112:115], v[170:173], v[88:91]
	v_mfma_f32_16x16x32_bf16 v[84:87], v[96:99], v[178:181], v[84:87]
	v_mfma_f32_16x16x32_bf16 v[76:79], v[96:99], v[190:193], v[76:79]
	v_mfma_f32_16x16x32_bf16 v[72:75], v[112:115], v[190:193], v[72:75]
	v_mfma_f32_16x16x32_bf16 v[92:95], v[100:103], v[174:177], v[92:95]
	v_mfma_f32_16x16x32_bf16 v[88:91], v[158:161], v[174:177], v[88:91]
	v_mfma_f32_16x16x32_bf16 v[84:87], v[100:103], v[186:189], v[84:87]
	v_mfma_f32_16x16x32_bf16 v[80:83], v[112:115], v[178:181], v[80:83]
	v_mfma_f32_16x16x32_bf16 v[76:79], v[100:103], v[194:197], v[76:79]
	v_mfma_f32_16x16x32_bf16 v[72:75], v[158:161], v[194:197], v[72:75]
	v_mfma_f32_16x16x32_bf16 v[68:71], v[96:99], v[198:201], v[68:71]
	v_mfma_f32_16x16x32_bf16 v[64:67], v[112:115], v[198:201], v[64:67]
	v_mfma_f32_16x16x32_bf16 v[170:173], v[158:161], v[186:189], v[80:83]
	v_mfma_f32_16x16x32_bf16 v[174:177], v[100:103], v[202:205], v[68:71]
	v_mfma_f32_16x16x32_bf16 v[178:181], v[158:161], v[202:205], v[64:67]
	s_barrier
; #define WAIT_V(n) asm volatile("s_waitcnt vmcnt(" #n ")" ::: "memory")
; #define WAIT_L(n) asm volatile("s_waitcnt lgkmcnt(" #n ")" ::: "memory")
; #define BAR __builtin_amdgcn_s_barrier()
;     ...
;     LDA(At, 0, 1); WAIT_V(4); BAR; WAIT_L(0); MMA(1, 0, At, B0); MMA(1, 1, At, B1); BAR; }
;   { LDB(B0, 1, 0); LDA(At, 1, 0); WAIT_V(2); BAR; WAIT_L(0); MMA(0, 0, At, B0); BAR;
	s_nop 2
	ds_read_b128 v[64:67], v144 offset:16384
	ds_read_b128 v[68:71], v144 offset:17408
	ds_read_b128 v[80:83], v141 offset:16384
	ds_read_b128 v[186:189], v141 offset:17408
	ds_read_b128 v[190:193], v140 offset:16384
	ds_read_b128 v[194:197], v140 offset:17408
	ds_read_b128 v[198:201], v139 offset:16384
	ds_read_b128 v[202:205], v139 offset:17408
	s_waitcnt vmcnt(4)
	s_barrier
	s_waitcnt lgkmcnt(0)
	s_waitcnt lgkmcnt(0)
	v_mfma_f32_16x16x32_bf16 v[60:63], v[130:133], v[64:67], v[60:63]
	v_mfma_f32_16x16x32_bf16 v[56:59], v[154:157], v[64:67], v[56:59]
	v_mfma_f32_16x16x32_bf16 v[52:55], v[130:133], v[80:83], v[52:55]
	v_mfma_f32_16x16x32_bf16 v[44:47], v[130:133], v[190:193], v[44:47]
	v_mfma_f32_16x16x32_bf16 v[40:43], v[154:157], v[190:193], v[40:43]
	v_mfma_f32_16x16x32_bf16 v[60:63], v[134:137], v[68:71], v[60:63]
	v_mfma_f32_16x16x32_bf16 v[56:59], v[166:169], v[68:71], v[56:59]
	v_mfma_f32_16x16x32_bf16 v[52:55], v[134:137], v[186:189], v[52:55]
	v_mfma_f32_16x16x32_bf16 v[48:51], v[154:157], v[80:83], v[48:51]
	v_mfma_f32_16x16x32_bf16 v[44:47], v[134:137], v[194:197], v[44:47]
	v_mfma_f32_16x16x32_bf16 v[40:43], v[166:169], v[194:197], v[40:43]
	v_mfma_f32_16x16x32_bf16 v[36:39], v[130:133], v[198:201], v[36:39]
	v_mfma_f32_16x16x32_bf16 v[32:35], v[154:157], v[198:201], v[32:35]
	v_mfma_f32_16x16x32_bf16 v[214:217], v[166:169], v[186:189], v[48:51]
	v_mfma_f32_16x16x32_bf16 v[128:131], v[134:137], v[202:205], v[36:39]
	v_mfma_f32_16x16x32_bf16 v[132:135], v[166:169], v[202:205], v[32:35]
	v_mfma_f32_16x16x32_bf16 v[28:31], v[96:99], v[64:67], v[28:31]
	v_mfma_f32_16x16x32_bf16 v[24:27], v[112:115], v[64:67], v[24:27]
	v_mfma_f32_16x16x32_bf16 v[20:23], v[96:99], v[80:83], v[20:23]
	v_mfma_f32_16x16x32_bf16 v[12:15], v[96:99], v[190:193], v[12:15]
	v_mfma_f32_16x16x32_bf16 v[8:11], v[112:115], v[190:193], v[8:11]
	v_mfma_f32_16x16x32_bf16 v[28:31], v[100:103], v[68:71], v[28:31]
	v_mfma_f32_16x16x32_bf16 v[24:27], v[158:161], v[68:71], v[24:27]
	v_mfma_f32_16x16x32_bf16 v[20:23], v[100:103], v[186:189], v[20:23]
	v_mfma_f32_16x16x32_bf16 v[16:19], v[112:115], v[80:83], v[16:19]
	v_mfma_f32_16x16x32_bf16 v[12:15], v[100:103], v[194:197], v[12:15]
	v_mfma_f32_16x16x32_bf16 v[8:11], v[158:161], v[194:197], v[8:11]
	v_mfma_f32_16x16x32_bf16 v[4:7], v[96:99], v[198:201], v[4:7]
	v_mfma_f32_16x16x32_bf16 v[0:3], v[112:115], v[198:201], v[0:3]
	v_mfma_f32_16x16x32_bf16 v[154:157], v[158:161], v[186:189], v[16:19]
	v_mfma_f32_16x16x32_bf16 v[166:169], v[100:103], v[202:205], v[4:7]
	v_mfma_f32_16x16x32_bf16 v[158:161], v[158:161], v[202:205], v[0:3]
	s_barrier
	s_nop 2
	ds_read_b128 v[0:3], v152
	ds_read_b128 v[4:7], v152 offset:1024
	ds_read_b128 v[16:19], v152 offset:2048
	ds_read_b128 v[150:153], v152 offset:3072
	ds_read_b128 v[32:35], v144 offset:32768
	ds_read_b128 v[36:39], v144 offset:33792
	ds_read_b128 v[48:51], v141 offset:32768
	ds_read_b128 v[68:71], v141 offset:33792
	ds_read_b128 v[186:189], v140 offset:32768
	ds_read_b128 v[190:193], v140 offset:33792
	ds_read_b128 v[194:197], v139 offset:32768
	ds_read_b128 v[198:201], v139 offset:33792
	s_waitcnt vmcnt(2)
	s_barrier
	s_waitcnt lgkmcnt(0)
	s_waitcnt lgkmcnt(0)
	v_mfma_f32_16x16x32_bf16 v[64:67], v[0:3], v[32:35], v[124:127]
	v_mfma_f32_16x16x32_bf16 v[112:115], v[4:7], v[36:39], v[64:67]
	v_mfma_f32_16x16x32_bf16 v[64:67], v[16:19], v[32:35], v[120:123]
	v_mfma_f32_16x16x32_bf16 v[96:99], v[150:153], v[36:39], v[64:67]
	v_mfma_f32_16x16x32_bf16 v[64:67], v[0:3], v[48:51], v[116:119]
	v_mfma_f32_16x16x32_bf16 v[116:119], v[4:7], v[68:71], v[64:67]
	v_mfma_f32_16x16x32_bf16 v[64:67], v[16:19], v[48:51], v[162:165]
	v_mfma_f32_16x16x32_bf16 v[100:103], v[150:153], v[68:71], v[64:67]
	v_mfma_f32_16x16x32_bf16 v[64:67], v[0:3], v[186:189], v[108:111]
	v_mfma_f32_16x16x32_bf16 v[120:123], v[4:7], v[190:193], v[64:67]
	v_mfma_f32_16x16x32_bf16 v[64:67], v[16:19], v[186:189], v[104:107]
	v_mfma_f32_16x16x32_bf16 v[104:107], v[150:153], v[190:193], v[64:67]
	v_mfma_f32_16x16x32_bf16 v[64:67], v[0:3], v[194:197], v[206:209]
	v_mfma_f32_16x16x32_bf16 v[124:127], v[4:7], v[198:201], v[64:67]
	v_mfma_f32_16x16x32_bf16 v[64:67], v[16:19], v[194:197], v[210:213]
	v_mfma_f32_16x16x32_bf16 v[108:111], v[150:153], v[198:201], v[64:67]
	s_barrier
; #define WAIT_V(n) asm volatile("s_waitcnt vmcnt(" #n ")" ::: "memory")
; #define WAIT_L(n) asm volatile("s_waitcnt lgkmcnt(" #n ")" ::: "memory")
; #define BAR __builtin_amdgcn_s_barrier()
;     ...
;     LDB(B1, 1, 1); WAIT_V(0); BAR; WAIT_L(0); MMA(0, 1, At, B1); BAR;
;     LDA(At, 1, 1); BAR; WAIT_L(0); MMA(1, 0, At, B0); MMA(1, 1, At, B1); BAR; }
;   if (wr == 0) BAR;
	ds_read_b128 v[162:165], v148
	ds_read_b128 v[202:205], v148 offset:1024
	ds_read_b128 v[206:209], v148 offset:2048
	ds_read_b128 v[146:149], v148 offset:3072
	s_waitcnt vmcnt(0)
	s_barrier
	s_waitcnt lgkmcnt(0)
	s_waitcnt lgkmcnt(0)
	v_mfma_f32_16x16x32_bf16 v[64:67], v[162:165], v[32:35], v[92:95]
	v_mfma_f32_16x16x32_bf16 v[32:35], v[206:209], v[32:35], v[88:91]
	v_mfma_f32_16x16x32_bf16 v[80:83], v[202:205], v[36:39], v[64:67]
	v_mfma_f32_16x16x32_bf16 v[64:67], v[146:149], v[36:39], v[32:35]
	v_mfma_f32_16x16x32_bf16 v[32:35], v[162:165], v[48:51], v[84:87]
	v_mfma_f32_16x16x32_bf16 v[84:87], v[202:205], v[68:71], v[32:35]
	v_mfma_f32_16x16x32_bf16 v[32:35], v[206:209], v[48:51], v[170:173]
	v_mfma_f32_16x16x32_bf16 v[68:71], v[146:149], v[68:71], v[32:35]
	v_mfma_f32_16x16x32_bf16 v[32:35], v[162:165], v[186:189], v[76:79]
	v_mfma_f32_16x16x32_bf16 v[88:91], v[202:205], v[190:193], v[32:35]
	v_mfma_f32_16x16x32_bf16 v[32:35], v[206:209], v[186:189], v[72:75]
	v_mfma_f32_16x16x32_bf16 v[72:75], v[146:149], v[190:193], v[32:35]
	v_mfma_f32_16x16x32_bf16 v[32:35], v[162:165], v[194:197], v[174:177]
	v_mfma_f32_16x16x32_bf16 v[92:95], v[202:205], v[198:201], v[32:35]
	v_mfma_f32_16x16x32_bf16 v[32:35], v[206:209], v[194:197], v[178:181]
	v_mfma_f32_16x16x32_bf16 v[76:79], v[146:149], v[198:201], v[32:35]
	s_barrier
	ds_read_b128 v[170:173], v144 offset:49152
	ds_read_b128 v[174:177], v144 offset:50176
	ds_read_b128 v[178:181], v141 offset:49152
	ds_read_b128 v[186:189], v141 offset:50176
	ds_read_b128 v[190:193], v140 offset:49152
	ds_read_b128 v[194:197], v140 offset:50176
	ds_read_b128 v[198:201], v139 offset:49152
	ds_read_b128 v[210:213], v139 offset:50176
	s_barrier
	s_waitcnt lgkmcnt(0)
	s_waitcnt lgkmcnt(0)
	v_mfma_f32_16x16x32_bf16 v[32:35], v[0:3], v[170:173], v[60:63]
	v_mfma_f32_16x16x32_bf16 v[36:39], v[0:3], v[178:181], v[52:55]
	v_mfma_f32_16x16x32_bf16 v[44:47], v[0:3], v[190:193], v[44:47]
	v_mfma_f32_16x16x32_bf16 v[0:3], v[0:3], v[198:201], v[128:131]
	v_mfma_f32_16x16x32_bf16 v[48:51], v[4:7], v[174:177], v[32:35]
	v_mfma_f32_16x16x32_bf16 v[32:35], v[16:19], v[170:173], v[56:59]
	v_mfma_f32_16x16x32_bf16 v[52:55], v[4:7], v[186:189], v[36:39]
	v_mfma_f32_16x16x32_bf16 v[36:39], v[16:19], v[178:181], v[214:217]
	v_mfma_f32_16x16x32_bf16 v[40:43], v[16:19], v[190:193], v[40:43]
	v_mfma_f32_16x16x32_bf16 v[60:63], v[4:7], v[210:213], v[0:3]
	v_mfma_f32_16x16x32_bf16 v[0:3], v[16:19], v[198:201], v[132:135]
	v_mfma_f32_16x16x32_bf16 v[32:35], v[150:153], v[174:177], v[32:35]
	v_mfma_f32_16x16x32_bf16 v[36:39], v[150:153], v[186:189], v[36:39]
	v_mfma_f32_16x16x32_bf16 v[56:59], v[4:7], v[194:197], v[44:47]
	v_mfma_f32_16x16x32_bf16 v[40:43], v[150:153], v[194:197], v[40:43]
	v_mfma_f32_16x16x32_bf16 v[44:47], v[150:153], v[210:213], v[0:3]
	v_mfma_f32_16x16x32_bf16 v[0:3], v[162:165], v[170:173], v[28:31]
	v_mfma_f32_16x16x32_bf16 v[12:15], v[162:165], v[190:193], v[12:15]
	v_mfma_f32_16x16x32_bf16 v[16:19], v[202:205], v[174:177], v[0:3]
	v_mfma_f32_16x16x32_bf16 v[0:3], v[206:209], v[170:173], v[24:27]
	v_mfma_f32_16x16x32_bf16 v[4:7], v[162:165], v[178:181], v[20:23]
	v_mfma_f32_16x16x32_bf16 v[24:27], v[202:205], v[194:197], v[12:15]
	v_mfma_f32_16x16x32_bf16 v[12:15], v[162:165], v[198:201], v[166:169]
	v_mfma_f32_16x16x32_bf16 v[20:23], v[202:205], v[186:189], v[4:7]
	v_mfma_f32_16x16x32_bf16 v[4:7], v[206:209], v[178:181], v[154:157]
	v_mfma_f32_16x16x32_bf16 v[8:11], v[206:209], v[190:193], v[8:11]
	v_mfma_f32_16x16x32_bf16 v[28:31], v[202:205], v[210:213], v[12:15]
	v_mfma_f32_16x16x32_bf16 v[12:15], v[206:209], v[198:201], v[158:161]
	v_mfma_f32_16x16x32_bf16 v[0:3], v[146:149], v[174:177], v[0:3]
	v_mfma_f32_16x16x32_bf16 v[4:7], v[146:149], v[186:189], v[4:7]
	v_mfma_f32_16x16x32_bf16 v[8:11], v[146:149], v[194:197], v[8:11]
	v_mfma_f32_16x16x32_bf16 v[12:15], v[146:149], v[210:213], v[12:15]
	v_cmp_gt_u32_e32 vcc, s57, v143
	s_barrier
	s_and_saveexec_b64 s[4:5], vcc
	s_cbranch_execz .LBB0_72
	s_barrier

; #define WAIT_L(n) asm volatile("s_waitcnt lgkmcnt(" #n ")" ::: "memory")
; #define BAR __builtin_amdgcn_s_barrier()
; #define SCHED __builtin_amdgcn_sched_barrier(0)
;     ...
;   for (int t = 0; t < nt - 2; t += 2) {
;     LDB(B0, 0, 0); SCHED; LDA(At, 0, 0); STAGE(SA(1, 1), A, brow + HALF, t + 1);
;     WAIT_L(8); BAR; WAIT_L(0); MMA(0, 0, At, B0); BAR; SCHED;
;     LDB(B1, 0, 1); STAGE(SB(0, 0), Bt, bcol, t + 2);
;     BAR; WAIT_L(0); MMA(0, 1, At, B1); BAR;
;     LDA(At, 0, 1); STAGE(SA(0, 0), A, brow, t + 2);
;     BAR; WAIT_L(0); MMA(1, 0, At, B0); BAR; SCHED;
.LBB0_1142:
	ds_read_b128 v[172:175], v169
	ds_read_b128 v[176:179], v169 offset:1024
	ds_read_b128 v[180:183], v169 offset:2048
	ds_read_b128 v[184:187], v169 offset:3072
	v_add_u32_e32 v170, 0xc000, v154
	v_lshl_add_u64 v[236:237], v[134:135], 0, s[30:31]
	v_readfirstlane_b32 s27, v170
	v_add_u32_e32 v171, 0xe000, v154
	v_lshl_add_u64 v[220:221], v[236:237], 0, s[14:15]
	s_mov_b32 m0, s27
	v_lshl_add_u64 v[238:239], v[138:139], 0, s[30:31]
	v_readfirstlane_b32 s27, v171
	ds_read_b128 v[188:191], v147
	ds_read_b128 v[192:195], v147 offset:1024
	ds_read_b128 v[196:199], v146
	ds_read_b128 v[200:203], v146 offset:1024
	ds_read_b128 v[204:207], v145
	ds_read_b128 v[208:211], v145 offset:1024
	ds_read_b128 v[212:215], v144
	ds_read_b128 v[216:219], v144 offset:1024
	global_load_lds_dwordx4 v[220:221], off
	v_lshl_add_u64 v[220:221], v[238:239], 0, s[14:15]
	s_mov_b32 m0, s27
	s_nop 0
	global_load_lds_dwordx4 v[220:221], off
	s_waitcnt lgkmcnt(8)
	s_barrier
	s_waitcnt lgkmcnt(0)
	s_waitcnt lgkmcnt(0)
	v_mfma_f32_16x16x32_bf16 v[124:127], v[172:175], v[188:191], v[124:127]
	v_mfma_f32_16x16x32_bf16 v[120:123], v[180:183], v[188:191], v[120:123]
	v_mfma_f32_16x16x32_bf16 v[116:119], v[172:175], v[196:199], v[116:119]
	v_mfma_f32_16x16x32_bf16 v[112:115], v[180:183], v[196:199], v[112:115]
	v_mfma_f32_16x16x32_bf16 v[108:111], v[172:175], v[204:207], v[108:111]
	v_mfma_f32_16x16x32_bf16 v[104:107], v[180:183], v[204:207], v[104:107]
	v_mfma_f32_16x16x32_bf16 v[100:103], v[172:175], v[212:215], v[100:103]
	v_mfma_f32_16x16x32_bf16 v[96:99], v[180:183], v[212:215], v[96:99]
	v_mfma_f32_16x16x32_bf16 v[124:127], v[176:179], v[192:195], v[124:127]
	v_mfma_f32_16x16x32_bf16 v[120:123], v[184:187], v[192:195], v[120:123]
	v_mfma_f32_16x16x32_bf16 v[116:119], v[176:179], v[200:203], v[116:119]
	v_mfma_f32_16x16x32_bf16 v[112:115], v[184:187], v[200:203], v[112:115]
	v_mfma_f32_16x16x32_bf16 v[108:111], v[176:179], v[208:211], v[108:111]
	v_mfma_f32_16x16x32_bf16 v[104:107], v[184:187], v[208:211], v[104:107]
	v_mfma_f32_16x16x32_bf16 v[100:103], v[176:179], v[216:219], v[100:103]
	v_mfma_f32_16x16x32_bf16 v[96:99], v[184:187], v[216:219], v[96:99]
	s_barrier
	v_lshl_add_u64 v[240:241], v[130:131], 0, s[30:31]
	v_readfirstlane_b32 s27, v152
	v_lshl_add_u64 v[242:243], v[240:241], 0, s[16:17]
	s_mov_b32 m0, s27
	ds_read_b128 v[220:223], v168
	ds_read_b128 v[224:227], v168 offset:1024
	ds_read_b128 v[228:231], v168 offset:2048
	ds_read_b128 v[232:235], v168 offset:3072
	global_load_lds_dwordx4 v[242:243], off
	v_lshl_add_u64 v[242:243], v[132:133], 0, s[30:31]
	v_readfirstlane_b32 s27, v153
	v_lshl_add_u64 v[244:245], v[242:243], 0, s[16:17]
	s_mov_b32 m0, s27
	s_nop 0
	global_load_lds_dwordx4 v[244:245], off
	s_barrier
	s_waitcnt lgkmcnt(0)
	s_waitcnt lgkmcnt(0)
	v_mfma_f32_16x16x32_bf16 v[92:95], v[220:223], v[188:191], v[92:95]
	v_mfma_f32_16x16x32_bf16 v[88:91], v[228:231], v[188:191], v[88:91]
	v_mfma_f32_16x16x32_bf16 v[84:87], v[220:223], v[196:199], v[84:87]
	v_mfma_f32_16x16x32_bf16 v[80:83], v[228:231], v[196:199], v[80:83]
	v_mfma_f32_16x16x32_bf16 v[76:79], v[220:223], v[204:207], v[76:79]
	v_mfma_f32_16x16x32_bf16 v[72:75], v[228:231], v[204:207], v[72:75]
	v_mfma_f32_16x16x32_bf16 v[68:71], v[220:223], v[212:215], v[68:71]
	v_mfma_f32_16x16x32_bf16 v[64:67], v[228:231], v[212:215], v[64:67]
	v_mfma_f32_16x16x32_bf16 v[92:95], v[224:227], v[192:195], v[92:95]
	v_mfma_f32_16x16x32_bf16 v[88:91], v[232:235], v[192:195], v[88:91]
	v_mfma_f32_16x16x32_bf16 v[84:87], v[224:227], v[200:203], v[84:87]
	v_mfma_f32_16x16x32_bf16 v[80:83], v[232:235], v[200:203], v[80:83]
	v_mfma_f32_16x16x32_bf16 v[76:79], v[224:227], v[208:211], v[76:79]
	v_mfma_f32_16x16x32_bf16 v[72:75], v[232:235], v[208:211], v[72:75]
	v_mfma_f32_16x16x32_bf16 v[68:71], v[224:227], v[216:219], v[68:71]
	v_mfma_f32_16x16x32_bf16 v[64:67], v[232:235], v[216:219], v[64:67]
	v_readfirstlane_b32 s27, v154
	v_lshl_add_u64 v[244:245], v[236:237], 0, s[16:17]
	s_mov_b32 m0, s27
	v_readfirstlane_b32 s27, v156
	s_barrier
	ds_read_b128 v[188:191], v147 offset:16384
	ds_read_b128 v[192:195], v147 offset:17408
	ds_read_b128 v[196:199], v146 offset:16384
	ds_read_b128 v[200:203], v146 offset:17408
	ds_read_b128 v[204:207], v145 offset:16384
	ds_read_b128 v[208:211], v145 offset:17408
	ds_read_b128 v[212:215], v144 offset:16384
	ds_read_b128 v[216:219], v144 offset:17408
	global_load_lds_dwordx4 v[244:245], off
	v_lshl_add_u64 v[244:245], v[238:239], 0, s[16:17]
	s_mov_b32 m0, s27
	s_nop 0
	global_load_lds_dwordx4 v[244:245], off
	s_barrier
	s_waitcnt lgkmcnt(0)
	s_waitcnt lgkmcnt(0)
	v_mfma_f32_16x16x32_bf16 v[60:63], v[172:175], v[188:191], v[60:63]
	v_mfma_f32_16x16x32_bf16 v[56:59], v[180:183], v[188:191], v[56:59]
	v_mfma_f32_16x16x32_bf16 v[52:55], v[172:175], v[196:199], v[52:55]
	v_mfma_f32_16x16x32_bf16 v[48:51], v[180:183], v[196:199], v[48:51]
	v_mfma_f32_16x16x32_bf16 v[44:47], v[172:175], v[204:207], v[44:47]
	v_mfma_f32_16x16x32_bf16 v[40:43], v[180:183], v[204:207], v[40:43]
	v_mfma_f32_16x16x32_bf16 v[36:39], v[172:175], v[212:215], v[36:39]
	v_mfma_f32_16x16x32_bf16 v[32:35], v[180:183], v[212:215], v[32:35]
	v_mfma_f32_16x16x32_bf16 v[60:63], v[176:179], v[192:195], v[60:63]
	v_mfma_f32_16x16x32_bf16 v[56:59], v[184:187], v[192:195], v[56:59]
	v_mfma_f32_16x16x32_bf16 v[52:55], v[176:179], v[200:203], v[52:55]
	v_mfma_f32_16x16x32_bf16 v[48:51], v[184:187], v[200:203], v[48:51]
	v_mfma_f32_16x16x32_bf16 v[44:47], v[176:179], v[208:211], v[44:47]
	v_mfma_f32_16x16x32_bf16 v[40:43], v[184:187], v[208:211], v[40:43]
	v_mfma_f32_16x16x32_bf16 v[36:39], v[176:179], v[216:219], v[36:39]
	v_mfma_f32_16x16x32_bf16 v[32:35], v[184:187], v[216:219], v[32:35]
	s_barrier
; #define WAIT_V(n) asm volatile("s_waitcnt vmcnt(" #n ")" ::: "memory")
; #define WAIT_L(n) asm volatile("s_waitcnt lgkmcnt(" #n ")" ::: "memory")
; #define BAR __builtin_amdgcn_s_barrier()
; #define SCHED __builtin_amdgcn_sched_barrier(0)
;     ...
;     STAGE(SB(0, 1), Bt, bcol1, t + 2);
;     WAIT_V(6); BAR; MMA(1, 1, At, B1); BAR;
;     LDB(B0, 1, 0); SCHED; LDA(At, 1, 0); STAGE(SA(0, 1), A, brow + HALF, t + 2);
;     WAIT_L(8); BAR; WAIT_L(0); MMA(0, 0, At, B0); BAR; SCHED;
;     LDB(B1, 1, 1); STAGE(SB(1, 0), Bt, bcol, t + 3);
;     BAR; WAIT_L(0); MMA(0, 1, At, B1); BAR;
;     LDA(At, 1, 1); STAGE(SA(1, 0), A, brow, t + 3);
	v_readfirstlane_b32 s27, v157
	v_lshl_add_u64 v[172:173], v[240:241], 0, s[18:19]
	s_mov_b32 m0, s27
	v_readfirstlane_b32 s27, v158
	global_load_lds_dwordx4 v[172:173], off
	v_lshl_add_u64 v[172:173], v[242:243], 0, s[18:19]
	s_mov_b32 m0, s27
	s_nop 0
	global_load_lds_dwordx4 v[172:173], off
	s_waitcnt vmcnt(6)
	s_barrier
	v_mfma_f32_16x16x32_bf16 v[28:31], v[220:223], v[188:191], v[28:31]
	v_mfma_f32_16x16x32_bf16 v[24:27], v[228:231], v[188:191], v[24:27]
	v_mfma_f32_16x16x32_bf16 v[20:23], v[220:223], v[196:199], v[20:23]
	v_mfma_f32_16x16x32_bf16 v[16:19], v[228:231], v[196:199], v[16:19]
	v_mfma_f32_16x16x32_bf16 v[12:15], v[220:223], v[204:207], v[12:15]
	v_mfma_f32_16x16x32_bf16 v[8:11], v[228:231], v[204:207], v[8:11]
	v_mfma_f32_16x16x32_bf16 v[4:7], v[220:223], v[212:215], v[4:7]
	v_mfma_f32_16x16x32_bf16 v[0:3], v[228:231], v[212:215], v[0:3]
	v_mfma_f32_16x16x32_bf16 v[28:31], v[224:227], v[192:195], v[28:31]
	v_mfma_f32_16x16x32_bf16 v[24:27], v[232:235], v[192:195], v[24:27]
	v_mfma_f32_16x16x32_bf16 v[20:23], v[224:227], v[200:203], v[20:23]
	v_mfma_f32_16x16x32_bf16 v[16:19], v[232:235], v[200:203], v[16:19]
	v_mfma_f32_16x16x32_bf16 v[12:15], v[224:227], v[208:211], v[12:15]
	v_mfma_f32_16x16x32_bf16 v[8:11], v[232:235], v[208:211], v[8:11]
	v_mfma_f32_16x16x32_bf16 v[4:7], v[224:227], v[216:219], v[4:7]
	v_mfma_f32_16x16x32_bf16 v[0:3], v[232:235], v[216:219], v[0:3]
	s_barrier
	ds_read_b128 v[172:175], v160
	ds_read_b128 v[176:179], v160 offset:1024
	ds_read_b128 v[180:183], v160 offset:2048
	ds_read_b128 v[184:187], v160 offset:3072
	v_readfirstlane_b32 s27, v159
	v_lshl_add_u64 v[220:221], v[236:237], 0, s[18:19]
	s_mov_b32 m0, s27
	v_readfirstlane_b32 s27, v161
	ds_read_b128 v[188:191], v147 offset:32768
	ds_read_b128 v[192:195], v147 offset:33792
	ds_read_b128 v[196:199], v146 offset:32768
	ds_read_b128 v[200:203], v146 offset:33792
	ds_read_b128 v[204:207], v145 offset:32768
	ds_read_b128 v[208:211], v145 offset:33792
	ds_read_b128 v[212:215], v144 offset:32768
	ds_read_b128 v[216:219], v144 offset:33792
	global_load_lds_dwordx4 v[220:221], off
	v_lshl_add_u64 v[220:221], v[238:239], 0, s[18:19]
	s_mov_b32 m0, s27
	s_nop 0
	global_load_lds_dwordx4 v[220:221], off
	s_waitcnt lgkmcnt(8)
	s_barrier
	s_waitcnt lgkmcnt(0)
	s_waitcnt lgkmcnt(0)
	v_mfma_f32_16x16x32_bf16 v[124:127], v[172:175], v[188:191], v[124:127]
	v_mfma_f32_16x16x32_bf16 v[120:123], v[180:183], v[188:191], v[120:123]
	v_mfma_f32_16x16x32_bf16 v[116:119], v[172:175], v[196:199], v[116:119]
	v_mfma_f32_16x16x32_bf16 v[112:115], v[180:183], v[196:199], v[112:115]
	v_mfma_f32_16x16x32_bf16 v[108:111], v[172:175], v[204:207], v[108:111]
	v_mfma_f32_16x16x32_bf16 v[104:107], v[180:183], v[204:207], v[104:107]
	v_mfma_f32_16x16x32_bf16 v[100:103], v[172:175], v[212:215], v[100:103]
	v_mfma_f32_16x16x32_bf16 v[96:99], v[180:183], v[212:215], v[96:99]
	v_mfma_f32_16x16x32_bf16 v[124:127], v[176:179], v[192:195], v[124:127]
	v_mfma_f32_16x16x32_bf16 v[120:123], v[184:187], v[192:195], v[120:123]
	v_mfma_f32_16x16x32_bf16 v[116:119], v[176:179], v[200:203], v[116:119]
	v_mfma_f32_16x16x32_bf16 v[112:115], v[184:187], v[200:203], v[112:115]
	v_mfma_f32_16x16x32_bf16 v[108:111], v[176:179], v[208:211], v[108:111]
	v_mfma_f32_16x16x32_bf16 v[104:107], v[184:187], v[208:211], v[104:107]
	v_mfma_f32_16x16x32_bf16 v[100:103], v[176:179], v[216:219], v[100:103]
	v_mfma_f32_16x16x32_bf16 v[96:99], v[184:187], v[216:219], v[96:99]
	s_barrier
	v_readfirstlane_b32 s27, v162
	v_lshl_add_u64 v[244:245], v[240:241], 0, s[20:21]
	s_mov_b32 m0, s27
	v_readfirstlane_b32 s27, v163
	ds_read_b128 v[220:223], v155
	ds_read_b128 v[224:227], v155 offset:1024
	ds_read_b128 v[228:231], v155 offset:2048
	ds_read_b128 v[232:235], v155 offset:3072
	global_load_lds_dwordx4 v[244:245], off
	v_lshl_add_u64 v[244:245], v[242:243], 0, s[20:21]
	s_mov_b32 m0, s27
	s_nop 0
	global_load_lds_dwordx4 v[244:245], off
	s_barrier
	s_waitcnt lgkmcnt(0)
	s_waitcnt lgkmcnt(0)
	v_mfma_f32_16x16x32_bf16 v[92:95], v[220:223], v[188:191], v[92:95]
	v_mfma_f32_16x16x32_bf16 v[88:91], v[228:231], v[188:191], v[88:91]
	v_mfma_f32_16x16x32_bf16 v[84:87], v[220:223], v[196:199], v[84:87]
	v_mfma_f32_16x16x32_bf16 v[80:83], v[228:231], v[196:199], v[80:83]
	v_mfma_f32_16x16x32_bf16 v[76:79], v[220:223], v[204:207], v[76:79]
	v_mfma_f32_16x16x32_bf16 v[72:75], v[228:231], v[204:207], v[72:75]
	v_mfma_f32_16x16x32_bf16 v[68:71], v[220:223], v[212:215], v[68:71]
	v_mfma_f32_16x16x32_bf16 v[64:67], v[228:231], v[212:215], v[64:67]
	v_mfma_f32_16x16x32_bf16 v[92:95], v[224:227], v[192:195], v[92:95]
	v_mfma_f32_16x16x32_bf16 v[88:91], v[232:235], v[192:195], v[88:91]
	v_mfma_f32_16x16x32_bf16 v[84:87], v[224:227], v[200:203], v[84:87]
	v_mfma_f32_16x16x32_bf16 v[80:83], v[232:235], v[200:203], v[80:83]
	v_mfma_f32_16x16x32_bf16 v[76:79], v[224:227], v[208:211], v[76:79]
	v_mfma_f32_16x16x32_bf16 v[72:75], v[232:235], v[208:211], v[72:75]
	v_mfma_f32_16x16x32_bf16 v[68:71], v[224:227], v[216:219], v[68:71]
	v_mfma_f32_16x16x32_bf16 v[64:67], v[232:235], v[216:219], v[64:67]
	v_readfirstlane_b32 s27, v164
	v_lshl_add_u64 v[236:237], v[236:237], 0, s[20:21]
	s_mov_b32 m0, s27
	v_readfirstlane_b32 s27, v165
	s_barrier
	ds_read_b128 v[188:191], v147 offset:49152
	ds_read_b128 v[192:195], v147 offset:50176
	ds_read_b128 v[196:199], v146 offset:49152
	ds_read_b128 v[200:203], v146 offset:50176
	ds_read_b128 v[204:207], v145 offset:49152
	ds_read_b128 v[208:211], v145 offset:50176
	ds_read_b128 v[212:215], v144 offset:49152
	ds_read_b128 v[216:219], v144 offset:50176
	global_load_lds_dwordx4 v[236:237], off
	v_lshl_add_u64 v[236:237], v[238:239], 0, s[20:21]
	s_mov_b32 m0, s27
	s_nop 0
	global_load_lds_dwordx4 v[236:237], off
	s_barrier
; #define WAIT_V(n) asm volatile("s_waitcnt vmcnt(" #n ")" ::: "memory")
; #define WAIT_L(n) asm volatile("s_waitcnt lgkmcnt(" #n ")" ::: "memory")
; #define BAR __builtin_amdgcn_s_barrier()
; #define SCHED __builtin_amdgcn_sched_barrier(0)
;     ...
;     BAR; WAIT_L(0); MMA(1, 0, At, B0); BAR; SCHED;
;     STAGE(SB(1, 1), Bt, bcol1, t + 3);
;     WAIT_V(6); BAR; MMA(1, 1, At, B1); BAR;
;   }
;   { LDB(B0, 0, 0); LDA(At, 0, 0); STAGE(SA(1, 1), A, brow + HALF, nt - 1);
;     BAR; WAIT_L(0); MMA(0, 0, At, B0); BAR;
;     LDB(B1, 0, 1); BAR; WAIT_L(0); MMA(0, 1, At, B1); BAR;
	s_waitcnt lgkmcnt(0)
	s_waitcnt lgkmcnt(0)
	v_mfma_f32_16x16x32_bf16 v[60:63], v[172:175], v[188:191], v[60:63]
	v_mfma_f32_16x16x32_bf16 v[56:59], v[180:183], v[188:191], v[56:59]
	v_mfma_f32_16x16x32_bf16 v[52:55], v[172:175], v[196:199], v[52:55]
	v_mfma_f32_16x16x32_bf16 v[48:51], v[180:183], v[196:199], v[48:51]
	v_mfma_f32_16x16x32_bf16 v[44:47], v[172:175], v[204:207], v[44:47]
	v_mfma_f32_16x16x32_bf16 v[40:43], v[180:183], v[204:207], v[40:43]
	v_mfma_f32_16x16x32_bf16 v[36:39], v[172:175], v[212:215], v[36:39]
	v_mfma_f32_16x16x32_bf16 v[32:35], v[180:183], v[212:215], v[32:35]
	v_mfma_f32_16x16x32_bf16 v[60:63], v[176:179], v[192:195], v[60:63]
	v_mfma_f32_16x16x32_bf16 v[56:59], v[184:187], v[192:195], v[56:59]
	v_mfma_f32_16x16x32_bf16 v[52:55], v[176:179], v[200:203], v[52:55]
	v_mfma_f32_16x16x32_bf16 v[48:51], v[184:187], v[200:203], v[48:51]
	v_mfma_f32_16x16x32_bf16 v[44:47], v[176:179], v[208:211], v[44:47]
	v_mfma_f32_16x16x32_bf16 v[40:43], v[184:187], v[208:211], v[40:43]
	v_mfma_f32_16x16x32_bf16 v[36:39], v[176:179], v[216:219], v[36:39]
	v_mfma_f32_16x16x32_bf16 v[32:35], v[184:187], v[216:219], v[32:35]
	s_barrier
	v_readfirstlane_b32 s27, v166
	v_lshl_add_u64 v[172:173], v[240:241], 0, s[22:23]
	s_mov_b32 m0, s27
	v_readfirstlane_b32 s27, v167
	global_load_lds_dwordx4 v[172:173], off
	v_lshl_add_u64 v[172:173], v[242:243], 0, s[22:23]
	s_mov_b32 m0, s27
	s_nop 0
	global_load_lds_dwordx4 v[172:173], off
	s_waitcnt vmcnt(6)
	s_barrier
	v_mfma_f32_16x16x32_bf16 v[28:31], v[220:223], v[188:191], v[28:31]
	v_mfma_f32_16x16x32_bf16 v[24:27], v[228:231], v[188:191], v[24:27]
	v_mfma_f32_16x16x32_bf16 v[20:23], v[220:223], v[196:199], v[20:23]
	v_mfma_f32_16x16x32_bf16 v[16:19], v[228:231], v[196:199], v[16:19]
	v_mfma_f32_16x16x32_bf16 v[12:15], v[220:223], v[204:207], v[12:15]
	v_mfma_f32_16x16x32_bf16 v[8:11], v[228:231], v[204:207], v[8:11]
	v_mfma_f32_16x16x32_bf16 v[4:7], v[220:223], v[212:215], v[4:7]
	v_mfma_f32_16x16x32_bf16 v[0:3], v[228:231], v[212:215], v[0:3]
	v_mfma_f32_16x16x32_bf16 v[28:31], v[224:227], v[192:195], v[28:31]
	v_mfma_f32_16x16x32_bf16 v[24:27], v[232:235], v[192:195], v[24:27]
	v_mfma_f32_16x16x32_bf16 v[20:23], v[224:227], v[200:203], v[20:23]
	v_mfma_f32_16x16x32_bf16 v[16:19], v[232:235], v[200:203], v[16:19]
	v_mfma_f32_16x16x32_bf16 v[12:15], v[224:227], v[208:211], v[12:15]
	v_mfma_f32_16x16x32_bf16 v[8:11], v[232:235], v[208:211], v[8:11]
	v_mfma_f32_16x16x32_bf16 v[4:7], v[224:227], v[216:219], v[4:7]
	v_mfma_f32_16x16x32_bf16 v[0:3], v[232:235], v[216:219], v[0:3]
	s_add_i32 s25, s25, 2
	s_add_u32 s30, s30, 0x100
	s_addc_u32 s31, s31, 0
	s_cmp_lt_u32 s25, 60
	s_barrier
	s_cbranch_scc1 .LBB0_1142
	s_add_u32 s28, s28, 0x1f80
	s_addc_u32 s29, s29, 0
	v_readfirstlane_b32 s25, v170
	v_lshl_add_u64 v[134:135], s[28:29], 0, v[136:137]
	s_mov_b32 m0, s25
	v_readfirstlane_b32 s25, v171
	ds_read_b128 v[130:133], v169
	ds_read_b128 v[156:159], v169 offset:1024
	ds_read_b128 v[162:165], v169 offset:2048
	ds_read_b128 v[172:175], v169 offset:3072
	ds_read_b128 v[176:179], v147
	ds_read_b128 v[180:183], v147 offset:1024
	ds_read_b128 v[184:187], v146
	ds_read_b128 v[188:191], v146 offset:1024
	ds_read_b128 v[192:195], v145
	ds_read_b128 v[196:199], v145 offset:1024
	ds_read_b128 v[200:203], v144
	ds_read_b128 v[204:207], v144 offset:1024
	global_load_lds_dwordx4 v[134:135], off
	v_lshl_add_u64 v[128:129], s[28:29], 0, v[128:129]
	s_mov_b32 m0, s25
	s_nop 0
	global_load_lds_dwordx4 v[128:129], off
	s_barrier
	s_waitcnt lgkmcnt(0)
	s_waitcnt lgkmcnt(0)
	v_mfma_f32_16x16x32_bf16 v[124:127], v[130:133], v[176:179], v[124:127]
	v_mfma_f32_16x16x32_bf16 v[120:123], v[162:165], v[176:179], v[120:123]
	v_mfma_f32_16x16x32_bf16 v[116:119], v[130:133], v[184:187], v[116:119]
	v_mfma_f32_16x16x32_bf16 v[112:115], v[162:165], v[184:187], v[112:115]
	v_mfma_f32_16x16x32_bf16 v[108:111], v[130:133], v[192:195], v[108:111]
	v_mfma_f32_16x16x32_bf16 v[104:107], v[162:165], v[192:195], v[104:107]
	v_mfma_f32_16x16x32_bf16 v[96:99], v[162:165], v[200:203], v[96:99]
	v_mfma_f32_16x16x32_bf16 v[124:127], v[156:159], v[180:183], v[124:127]
	v_mfma_f32_16x16x32_bf16 v[120:123], v[172:175], v[180:183], v[120:123]
	v_mfma_f32_16x16x32_bf16 v[116:119], v[156:159], v[188:191], v[116:119]
	v_mfma_f32_16x16x32_bf16 v[112:115], v[172:175], v[188:191], v[112:115]
	v_mfma_f32_16x16x32_bf16 v[108:111], v[156:159], v[196:199], v[108:111]
	v_mfma_f32_16x16x32_bf16 v[104:107], v[172:175], v[196:199], v[104:107]
	v_mfma_f32_16x16x32_bf16 v[100:103], v[130:133], v[200:203], v[100:103]
	v_mfma_f32_16x16x32_bf16 v[96:99], v[172:175], v[204:207], v[96:99]
	v_mfma_f32_16x16x32_bf16 v[100:103], v[156:159], v[204:207], v[100:103]
	s_barrier
	ds_read_b128 v[208:211], v168
	ds_read_b128 v[212:215], v168 offset:1024
	ds_read_b128 v[216:219], v168 offset:2048
	ds_read_b128 v[166:169], v168 offset:3072
	s_barrier
	s_waitcnt lgkmcnt(0)
	s_waitcnt lgkmcnt(0)
	v_mfma_f32_16x16x32_bf16 v[92:95], v[208:211], v[176:179], v[92:95]
	v_mfma_f32_16x16x32_bf16 v[88:91], v[216:219], v[176:179], v[88:91]
	v_mfma_f32_16x16x32_bf16 v[84:87], v[208:211], v[184:187], v[84:87]
	v_mfma_f32_16x16x32_bf16 v[80:83], v[216:219], v[184:187], v[80:83]
	v_mfma_f32_16x16x32_bf16 v[76:79], v[208:211], v[192:195], v[76:79]
	v_mfma_f32_16x16x32_bf16 v[72:75], v[216:219], v[192:195], v[72:75]
	v_mfma_f32_16x16x32_bf16 v[68:71], v[208:211], v[200:203], v[68:71]
	v_mfma_f32_16x16x32_bf16 v[92:95], v[212:215], v[180:183], v[92:95]
	v_mfma_f32_16x16x32_bf16 v[88:91], v[166:169], v[180:183], v[88:91]
	v_mfma_f32_16x16x32_bf16 v[84:87], v[212:215], v[188:191], v[84:87]
	v_mfma_f32_16x16x32_bf16 v[80:83], v[166:169], v[188:191], v[80:83]
	v_mfma_f32_16x16x32_bf16 v[76:79], v[212:215], v[196:199], v[76:79]
	v_mfma_f32_16x16x32_bf16 v[176:179], v[166:169], v[196:199], v[72:75]
	v_mfma_f32_16x16x32_bf16 v[68:71], v[212:215], v[204:207], v[68:71]
	v_mfma_f32_16x16x32_bf16 v[64:67], v[216:219], v[200:203], v[64:67]
	v_mfma_f32_16x16x32_bf16 v[180:183], v[166:169], v[204:207], v[64:67]
	s_barrier
; #define WAIT_V(n) asm volatile("s_waitcnt vmcnt(" #n ")" ::: "memory")
; #define WAIT_L(n) asm volatile("s_waitcnt lgkmcnt(" #n ")" ::: "memory")
; #define BAR __builtin_amdgcn_s_barrier()
;     ...
;     LDA(At, 0, 1); WAIT_V(4); BAR; WAIT_L(0); MMA(1, 0, At, B0); MMA(1, 1, At, B1); BAR; }
;   { LDB(B0, 1, 0); LDA(At, 1, 0); WAIT_V(2); BAR; WAIT_L(0); MMA(0, 0, At, B0); BAR;
	s_nop 4
	ds_read_b128 v[64:67], v147 offset:16384
	ds_read_b128 v[72:75], v147 offset:17408
	ds_read_b128 v[184:187], v146 offset:16384
	ds_read_b128 v[188:191], v146 offset:17408
	ds_read_b128 v[192:195], v145 offset:16384
	ds_read_b128 v[196:199], v145 offset:17408
	ds_read_b128 v[200:203], v144 offset:16384
	ds_read_b128 v[204:207], v144 offset:17408
	s_waitcnt vmcnt(4)
	s_barrier
	s_waitcnt lgkmcnt(0)
	s_waitcnt lgkmcnt(0)
	v_mfma_f32_16x16x32_bf16 v[60:63], v[130:133], v[64:67], v[60:63]
	v_mfma_f32_16x16x32_bf16 v[36:39], v[130:133], v[200:203], v[36:39]
	v_mfma_f32_16x16x32_bf16 v[32:35], v[162:165], v[200:203], v[32:35]
	v_mfma_f32_16x16x32_bf16 v[60:63], v[156:159], v[72:75], v[60:63]
	v_mfma_f32_16x16x32_bf16 v[56:59], v[162:165], v[64:67], v[56:59]
	v_mfma_f32_16x16x32_bf16 v[52:55], v[130:133], v[184:187], v[52:55]
	v_mfma_f32_16x16x32_bf16 v[48:51], v[162:165], v[184:187], v[48:51]
	v_mfma_f32_16x16x32_bf16 v[44:47], v[130:133], v[192:195], v[44:47]
	v_mfma_f32_16x16x32_bf16 v[40:43], v[162:165], v[192:195], v[40:43]
	v_mfma_f32_16x16x32_bf16 v[128:131], v[156:159], v[204:207], v[36:39]
	v_mfma_f32_16x16x32_bf16 v[132:135], v[172:175], v[204:207], v[32:35]
	v_mfma_f32_16x16x32_bf16 v[220:223], v[172:175], v[72:75], v[56:59]
	v_mfma_f32_16x16x32_bf16 v[224:227], v[156:159], v[188:191], v[52:55]
	v_mfma_f32_16x16x32_bf16 v[228:231], v[172:175], v[188:191], v[48:51]
	v_mfma_f32_16x16x32_bf16 v[232:235], v[156:159], v[196:199], v[44:47]
	v_mfma_f32_16x16x32_bf16 v[236:239], v[172:175], v[196:199], v[40:43]
	v_mfma_f32_16x16x32_bf16 v[28:31], v[208:211], v[64:67], v[28:31]
	v_mfma_f32_16x16x32_bf16 v[24:27], v[216:219], v[64:67], v[24:27]
	v_mfma_f32_16x16x32_bf16 v[20:23], v[208:211], v[184:187], v[20:23]
	v_mfma_f32_16x16x32_bf16 v[16:19], v[216:219], v[184:187], v[16:19]
	v_mfma_f32_16x16x32_bf16 v[12:15], v[208:211], v[192:195], v[12:15]
	v_mfma_f32_16x16x32_bf16 v[8:11], v[216:219], v[192:195], v[8:11]
	v_mfma_f32_16x16x32_bf16 v[4:7], v[208:211], v[200:203], v[4:7]
	v_mfma_f32_16x16x32_bf16 v[0:3], v[216:219], v[200:203], v[0:3]
	v_mfma_f32_16x16x32_bf16 v[156:159], v[212:215], v[72:75], v[28:31]
	v_mfma_f32_16x16x32_bf16 v[24:27], v[166:169], v[72:75], v[24:27]
	v_mfma_f32_16x16x32_bf16 v[162:165], v[212:215], v[188:191], v[20:23]
	v_mfma_f32_16x16x32_bf16 v[170:173], v[166:169], v[188:191], v[16:19]
	v_mfma_f32_16x16x32_bf16 v[12:15], v[212:215], v[196:199], v[12:15]
	v_mfma_f32_16x16x32_bf16 v[184:187], v[166:169], v[196:199], v[8:11]
	v_mfma_f32_16x16x32_bf16 v[188:191], v[212:215], v[204:207], v[4:7]
	v_mfma_f32_16x16x32_bf16 v[166:169], v[166:169], v[204:207], v[0:3]
	s_barrier
	ds_read_b128 v[192:195], v160
	ds_read_b128 v[196:199], v160 offset:1024
	ds_read_b128 v[200:203], v160 offset:2048
	ds_read_b128 v[204:207], v160 offset:3072
	ds_read_b128 v[32:35], v147 offset:32768
	ds_read_b128 v[48:51], v147 offset:33792
	ds_read_b128 v[52:55], v146 offset:32768
	ds_read_b128 v[64:67], v146 offset:33792
	ds_read_b128 v[208:211], v145 offset:32768
	ds_read_b128 v[212:215], v145 offset:33792
	ds_read_b128 v[216:219], v144 offset:32768
	ds_read_b128 v[240:243], v144 offset:33792
	s_waitcnt vmcnt(2)
	s_barrier
	s_waitcnt lgkmcnt(0)
	s_waitcnt lgkmcnt(0)
	v_mfma_f32_16x16x32_bf16 v[0:3], v[192:195], v[32:35], v[124:127]
	v_mfma_f32_16x16x32_bf16 v[4:7], v[200:203], v[32:35], v[120:123]
	v_mfma_f32_16x16x32_bf16 v[8:11], v[192:195], v[52:55], v[116:119]
	v_mfma_f32_16x16x32_bf16 v[16:19], v[200:203], v[52:55], v[112:115]
	v_mfma_f32_16x16x32_bf16 v[20:23], v[192:195], v[208:211], v[108:111]
	v_mfma_f32_16x16x32_bf16 v[28:31], v[200:203], v[208:211], v[104:107]
	v_mfma_f32_16x16x32_bf16 v[36:39], v[192:195], v[216:219], v[100:103]
	v_mfma_f32_16x16x32_bf16 v[40:43], v[200:203], v[216:219], v[96:99]
	v_mfma_f32_16x16x32_bf16 v[0:3], v[196:199], v[48:51], v[0:3]
	v_mfma_f32_16x16x32_bf16 v[4:7], v[204:207], v[48:51], v[4:7]
	v_mfma_f32_16x16x32_bf16 v[8:11], v[196:199], v[64:67], v[8:11]
	v_mfma_f32_16x16x32_bf16 v[16:19], v[204:207], v[64:67], v[16:19]
	v_mfma_f32_16x16x32_bf16 v[20:23], v[196:199], v[212:215], v[20:23]
	v_mfma_f32_16x16x32_bf16 v[28:31], v[204:207], v[212:215], v[28:31]
	v_mfma_f32_16x16x32_bf16 v[36:39], v[196:199], v[240:243], v[36:39]
	v_mfma_f32_16x16x32_bf16 v[44:47], v[204:207], v[240:243], v[40:43]
	s_barrier
; #define WAIT_V(n) asm volatile("s_waitcnt vmcnt(" #n ")" ::: "memory")
; #define WAIT_L(n) asm volatile("s_waitcnt lgkmcnt(" #n ")" ::: "memory")
; #define BAR __builtin_amdgcn_s_barrier()
;     ...
;     LDB(B1, 1, 1); WAIT_V(0); BAR; WAIT_L(0); MMA(0, 1, At, B1); BAR;
;     LDA(At, 1, 1); BAR; WAIT_L(0); MMA(1, 0, At, B0); MMA(1, 1, At, B1); BAR; }
;   if (wr == 0) BAR;
	ds_read_b128 v[244:247], v155
	ds_read_b128 v[248:251], v155 offset:1024
	ds_read_b128 v[100:103], v155 offset:2048
	ds_read_b128 v[152:155], v155 offset:3072
	s_waitcnt vmcnt(0)
	s_barrier
	s_waitcnt lgkmcnt(0)
	s_waitcnt lgkmcnt(0)
	v_mfma_f32_16x16x32_bf16 v[40:43], v[244:247], v[32:35], v[92:95]
	v_mfma_f32_16x16x32_bf16 v[32:35], v[100:103], v[32:35], v[88:91]
	v_mfma_f32_16x16x32_bf16 v[40:43], v[248:251], v[48:51], v[40:43]
	v_mfma_f32_16x16x32_bf16 v[32:35], v[152:155], v[48:51], v[32:35]
	v_mfma_f32_16x16x32_bf16 v[48:51], v[244:247], v[52:55], v[84:87]
	v_mfma_f32_16x16x32_bf16 v[56:59], v[248:251], v[64:67], v[48:51]
	v_mfma_f32_16x16x32_bf16 v[48:51], v[100:103], v[52:55], v[80:83]
	v_mfma_f32_16x16x32_bf16 v[52:55], v[244:247], v[208:211], v[76:79]
	v_mfma_f32_16x16x32_bf16 v[72:75], v[248:251], v[212:215], v[52:55]
	v_mfma_f32_16x16x32_bf16 v[52:55], v[100:103], v[208:211], v[176:179]
	v_mfma_f32_16x16x32_bf16 v[48:51], v[152:155], v[64:67], v[48:51]
	v_mfma_f32_16x16x32_bf16 v[64:67], v[152:155], v[212:215], v[52:55]
	v_mfma_f32_16x16x32_bf16 v[52:55], v[244:247], v[216:219], v[68:71]
	v_mfma_f32_16x16x32_bf16 v[88:91], v[248:251], v[240:243], v[52:55]
	v_mfma_f32_16x16x32_bf16 v[52:55], v[100:103], v[216:219], v[180:183]
	v_mfma_f32_16x16x32_bf16 v[76:79], v[152:155], v[240:243], v[52:55]
	s_barrier
	ds_read_b128 v[96:99], v147 offset:49152
	ds_read_b128 v[108:111], v147 offset:50176
	ds_read_b128 v[120:123], v146 offset:49152
	ds_read_b128 v[124:127], v146 offset:50176
	ds_read_b128 v[178:181], v145 offset:49152
	ds_read_b128 v[208:211], v145 offset:50176
	ds_read_b128 v[212:215], v144 offset:49152
	ds_read_b128 v[144:147], v144 offset:50176
	s_barrier
	s_waitcnt lgkmcnt(0)
	s_waitcnt lgkmcnt(0)
	v_mfma_f32_16x16x32_bf16 v[104:107], v[192:195], v[212:215], v[128:131]
	v_mfma_f32_16x16x32_bf16 v[52:55], v[192:195], v[96:99], v[60:63]
	v_mfma_f32_16x16x32_bf16 v[60:63], v[200:203], v[96:99], v[220:223]
	v_mfma_f32_16x16x32_bf16 v[68:71], v[192:195], v[120:123], v[224:227]
	v_mfma_f32_16x16x32_bf16 v[80:83], v[200:203], v[120:123], v[228:231]
	v_mfma_f32_16x16x32_bf16 v[84:87], v[192:195], v[178:181], v[232:235]
	v_mfma_f32_16x16x32_bf16 v[92:95], v[200:203], v[178:181], v[236:239]
	v_mfma_f32_16x16x32_bf16 v[174:177], v[196:199], v[144:147], v[104:107]
	v_mfma_f32_16x16x32_bf16 v[104:107], v[200:203], v[212:215], v[132:135]
	v_mfma_f32_16x16x32_bf16 v[52:55], v[196:199], v[108:111], v[52:55]
	v_mfma_f32_16x16x32_bf16 v[60:63], v[204:207], v[108:111], v[60:63]
	v_mfma_f32_16x16x32_bf16 v[68:71], v[196:199], v[124:127], v[68:71]
	v_mfma_f32_16x16x32_bf16 v[80:83], v[204:207], v[124:127], v[80:83]
	v_mfma_f32_16x16x32_bf16 v[84:87], v[196:199], v[208:211], v[84:87]
	v_mfma_f32_16x16x32_bf16 v[92:95], v[204:207], v[208:211], v[92:95]
	v_mfma_f32_16x16x32_bf16 v[112:115], v[204:207], v[144:147], v[104:107]
	v_mfma_f32_16x16x32_bf16 v[24:27], v[100:103], v[96:99], v[24:27]
	v_mfma_f32_16x16x32_bf16 v[104:107], v[244:247], v[96:99], v[156:159]
	v_mfma_f32_16x16x32_bf16 v[96:99], v[152:155], v[108:111], v[24:27]
	v_mfma_f32_16x16x32_bf16 v[24:27], v[244:247], v[120:123], v[162:165]
	v_mfma_f32_16x16x32_bf16 v[116:119], v[248:251], v[124:127], v[24:27]
	v_mfma_f32_16x16x32_bf16 v[24:27], v[100:103], v[120:123], v[170:173]
	v_mfma_f32_16x16x32_bf16 v[12:15], v[244:247], v[178:181], v[12:15]
	v_mfma_f32_16x16x32_bf16 v[104:107], v[248:251], v[108:111], v[104:107]
	v_mfma_f32_16x16x32_bf16 v[108:111], v[152:155], v[124:127], v[24:27]
	v_mfma_f32_16x16x32_bf16 v[124:127], v[248:251], v[208:211], v[12:15]
	v_mfma_f32_16x16x32_bf16 v[12:15], v[100:103], v[178:181], v[184:187]
	v_mfma_f32_16x16x32_bf16 v[120:123], v[152:155], v[208:211], v[12:15]
	v_mfma_f32_16x16x32_bf16 v[12:15], v[244:247], v[212:215], v[188:191]
	v_mfma_f32_16x16x32_bf16 v[132:135], v[248:251], v[144:147], v[12:15]
	v_mfma_f32_16x16x32_bf16 v[12:15], v[100:103], v[212:215], v[166:169]
	v_mfma_f32_16x16x32_bf16 v[128:131], v[152:155], v[144:147], v[12:15]
	v_cmp_gt_u32_e32 vcc, s41, v150
	s_barrier
	s_and_saveexec_b64 s[28:29], vcc
	s_cbranch_execz .LBB0_1145
	s_barrier

; #define WAIT_L(n) asm volatile("s_waitcnt lgkmcnt(" #n ")" ::: "memory")
; #define BAR __builtin_amdgcn_s_barrier()
; #define SCHED __builtin_amdgcn_sched_barrier(0)
;     ...
;   for (int t = 0; t < nt - 2; t += 2) {
;     LDB(B0, 0, 0); SCHED; LDA(At, 0, 0); STAGE(SA(1, 1), A, brow + HALF, t + 1);
;     WAIT_L(8); BAR; WAIT_L(0); MMA(0, 0, At, B0); BAR; SCHED;
;     LDB(B1, 0, 1); STAGE(SB(0, 0), Bt, bcol, t + 2);
;     BAR; WAIT_L(0); MMA(0, 1, At, B1); BAR;
;     LDA(At, 0, 1); STAGE(SA(0, 0), A, brow, t + 2);
;     BAR; WAIT_L(0); MMA(1, 0, At, B0); BAR; SCHED;
.LBB0_1236:
	ds_read_b128 v[176:179], v173
	ds_read_b128 v[180:183], v173 offset:1024
	ds_read_b128 v[184:187], v173 offset:2048
	ds_read_b128 v[188:191], v173 offset:3072
	v_add_u32_e32 v174, 0xc000, v154
	v_lshl_add_u64 v[240:241], v[134:135], 0, s[4:5]
	v_readfirstlane_b32 s12, v174
	v_add_u32_e32 v175, 0xe000, v154
	v_lshl_add_u64 v[224:225], v[240:241], 0, s[24:25]
	s_mov_b32 m0, s12
	v_lshl_add_u64 v[242:243], v[136:137], 0, s[4:5]
	v_readfirstlane_b32 s12, v175
	ds_read_b128 v[192:195], v153
	ds_read_b128 v[196:199], v153 offset:1024
	ds_read_b128 v[200:203], v152
	ds_read_b128 v[204:207], v152 offset:1024
	ds_read_b128 v[208:211], v151
	ds_read_b128 v[212:215], v151 offset:1024
	ds_read_b128 v[216:219], v150
	ds_read_b128 v[220:223], v150 offset:1024
	global_load_lds_dwordx4 v[224:225], off
	v_lshl_add_u64 v[224:225], v[242:243], 0, s[24:25]
	s_mov_b32 m0, s12
	s_nop 0
	global_load_lds_dwordx4 v[224:225], off
	s_waitcnt lgkmcnt(8)
	s_barrier
	s_waitcnt lgkmcnt(0)
	s_waitcnt lgkmcnt(0)
	v_mfma_f32_16x16x32_bf16 v[124:127], v[176:179], v[192:195], v[124:127]
	v_mfma_f32_16x16x32_bf16 v[120:123], v[184:187], v[192:195], v[120:123]
	v_mfma_f32_16x16x32_bf16 v[116:119], v[176:179], v[200:203], v[116:119]
	v_mfma_f32_16x16x32_bf16 v[112:115], v[184:187], v[200:203], v[112:115]
	v_mfma_f32_16x16x32_bf16 v[108:111], v[176:179], v[208:211], v[108:111]
	v_mfma_f32_16x16x32_bf16 v[104:107], v[184:187], v[208:211], v[104:107]
	v_mfma_f32_16x16x32_bf16 v[100:103], v[176:179], v[216:219], v[100:103]
	v_mfma_f32_16x16x32_bf16 v[96:99], v[184:187], v[216:219], v[96:99]
	v_mfma_f32_16x16x32_bf16 v[124:127], v[180:183], v[196:199], v[124:127]
	v_mfma_f32_16x16x32_bf16 v[120:123], v[188:191], v[196:199], v[120:123]
	v_mfma_f32_16x16x32_bf16 v[116:119], v[180:183], v[204:207], v[116:119]
	v_mfma_f32_16x16x32_bf16 v[112:115], v[188:191], v[204:207], v[112:115]
	v_mfma_f32_16x16x32_bf16 v[108:111], v[180:183], v[212:215], v[108:111]
	v_mfma_f32_16x16x32_bf16 v[104:107], v[188:191], v[212:215], v[104:107]
	v_mfma_f32_16x16x32_bf16 v[100:103], v[180:183], v[220:223], v[100:103]
	v_mfma_f32_16x16x32_bf16 v[96:99], v[188:191], v[220:223], v[96:99]
	s_barrier
	v_lshl_add_u64 v[244:245], v[130:131], 0, s[4:5]
	v_readfirstlane_b32 s12, v142
	v_lshl_add_u64 v[246:247], v[244:245], 0, s[26:27]
	s_mov_b32 m0, s12
	ds_read_b128 v[224:227], v172
	ds_read_b128 v[228:231], v172 offset:1024
	ds_read_b128 v[232:235], v172 offset:2048
	ds_read_b128 v[236:239], v172 offset:3072
	global_load_lds_dwordx4 v[246:247], off
	v_lshl_add_u64 v[246:247], v[132:133], 0, s[4:5]
	v_readfirstlane_b32 s12, v143
	v_lshl_add_u64 v[248:249], v[246:247], 0, s[26:27]
	s_mov_b32 m0, s12
	s_nop 0
	global_load_lds_dwordx4 v[248:249], off
	s_barrier
	s_waitcnt lgkmcnt(0)
	s_waitcnt lgkmcnt(0)
	v_mfma_f32_16x16x32_bf16 v[92:95], v[224:227], v[192:195], v[92:95]
	v_mfma_f32_16x16x32_bf16 v[88:91], v[232:235], v[192:195], v[88:91]
	v_mfma_f32_16x16x32_bf16 v[84:87], v[224:227], v[200:203], v[84:87]
	v_mfma_f32_16x16x32_bf16 v[80:83], v[232:235], v[200:203], v[80:83]
	v_mfma_f32_16x16x32_bf16 v[76:79], v[224:227], v[208:211], v[76:79]
	v_mfma_f32_16x16x32_bf16 v[72:75], v[232:235], v[208:211], v[72:75]
	v_mfma_f32_16x16x32_bf16 v[68:71], v[224:227], v[216:219], v[68:71]
	v_mfma_f32_16x16x32_bf16 v[64:67], v[232:235], v[216:219], v[64:67]
	v_mfma_f32_16x16x32_bf16 v[92:95], v[228:231], v[196:199], v[92:95]
	v_mfma_f32_16x16x32_bf16 v[88:91], v[236:239], v[196:199], v[88:91]
	v_mfma_f32_16x16x32_bf16 v[84:87], v[228:231], v[204:207], v[84:87]
	v_mfma_f32_16x16x32_bf16 v[80:83], v[236:239], v[204:207], v[80:83]
	v_mfma_f32_16x16x32_bf16 v[76:79], v[228:231], v[212:215], v[76:79]
	v_mfma_f32_16x16x32_bf16 v[72:75], v[236:239], v[212:215], v[72:75]
	v_mfma_f32_16x16x32_bf16 v[68:71], v[228:231], v[220:223], v[68:71]
	v_mfma_f32_16x16x32_bf16 v[64:67], v[236:239], v[220:223], v[64:67]
	v_readfirstlane_b32 s12, v154
	v_lshl_add_u64 v[248:249], v[240:241], 0, s[26:27]
	s_mov_b32 m0, s12
	v_readfirstlane_b32 s12, v155
	s_barrier
	ds_read_b128 v[192:195], v153 offset:16384
	ds_read_b128 v[196:199], v153 offset:17408
	ds_read_b128 v[200:203], v152 offset:16384
	ds_read_b128 v[204:207], v152 offset:17408
	ds_read_b128 v[208:211], v151 offset:16384
	ds_read_b128 v[212:215], v151 offset:17408
	ds_read_b128 v[216:219], v150 offset:16384
	ds_read_b128 v[220:223], v150 offset:17408
	global_load_lds_dwordx4 v[248:249], off
	v_lshl_add_u64 v[248:249], v[242:243], 0, s[26:27]
	s_mov_b32 m0, s12
	s_nop 0
	global_load_lds_dwordx4 v[248:249], off
	s_barrier
	s_waitcnt lgkmcnt(0)
	s_waitcnt lgkmcnt(0)
	v_mfma_f32_16x16x32_bf16 v[60:63], v[176:179], v[192:195], v[60:63]
	v_mfma_f32_16x16x32_bf16 v[56:59], v[184:187], v[192:195], v[56:59]
	v_mfma_f32_16x16x32_bf16 v[52:55], v[176:179], v[200:203], v[52:55]
	v_mfma_f32_16x16x32_bf16 v[48:51], v[184:187], v[200:203], v[48:51]
	v_mfma_f32_16x16x32_bf16 v[44:47], v[176:179], v[208:211], v[44:47]
	v_mfma_f32_16x16x32_bf16 v[40:43], v[184:187], v[208:211], v[40:43]
	v_mfma_f32_16x16x32_bf16 v[36:39], v[176:179], v[216:219], v[36:39]
	v_mfma_f32_16x16x32_bf16 v[32:35], v[184:187], v[216:219], v[32:35]
	v_mfma_f32_16x16x32_bf16 v[60:63], v[180:183], v[196:199], v[60:63]
	v_mfma_f32_16x16x32_bf16 v[56:59], v[188:191], v[196:199], v[56:59]
	v_mfma_f32_16x16x32_bf16 v[52:55], v[180:183], v[204:207], v[52:55]
	v_mfma_f32_16x16x32_bf16 v[48:51], v[188:191], v[204:207], v[48:51]
	v_mfma_f32_16x16x32_bf16 v[44:47], v[180:183], v[212:215], v[44:47]
	v_mfma_f32_16x16x32_bf16 v[40:43], v[188:191], v[212:215], v[40:43]
	v_mfma_f32_16x16x32_bf16 v[36:39], v[180:183], v[220:223], v[36:39]
	v_mfma_f32_16x16x32_bf16 v[32:35], v[188:191], v[220:223], v[32:35]
	s_barrier
; #define WAIT_V(n) asm volatile("s_waitcnt vmcnt(" #n ")" ::: "memory")
; #define WAIT_L(n) asm volatile("s_waitcnt lgkmcnt(" #n ")" ::: "memory")
; #define BAR __builtin_amdgcn_s_barrier()
; #define SCHED __builtin_amdgcn_sched_barrier(0)
;     ...
;     STAGE(SB(0, 1), Bt, bcol1, t + 2);
;     WAIT_V(6); BAR; MMA(1, 1, At, B1); BAR;
;     LDB(B0, 1, 0); SCHED; LDA(At, 1, 0); STAGE(SA(0, 1), A, brow + HALF, t + 2);
;     WAIT_L(8); BAR; WAIT_L(0); MMA(0, 0, At, B0); BAR; SCHED;
;     LDB(B1, 1, 1); STAGE(SB(1, 0), Bt, bcol, t + 3);
;     BAR; WAIT_L(0); MMA(0, 1, At, B1); BAR;
;     LDA(At, 1, 1); STAGE(SA(1, 0), A, brow, t + 3);
	v_lshl_add_u64 v[248:249], v[138:139], 0, s[4:5]
	v_readfirstlane_b32 s12, v157
	v_lshl_add_u64 v[176:177], v[248:249], 0, s[28:29]
	s_mov_b32 m0, s12
	v_lshl_add_u64 v[250:251], v[140:141], 0, s[4:5]
	v_readfirstlane_b32 s12, v158
	global_load_lds_dwordx4 v[176:177], off
	v_lshl_add_u64 v[176:177], v[250:251], 0, s[28:29]
	s_mov_b32 m0, s12
	s_nop 0
	global_load_lds_dwordx4 v[176:177], off
	s_waitcnt vmcnt(6)
	s_barrier
	v_mfma_f32_16x16x32_bf16 v[28:31], v[224:227], v[192:195], v[28:31]
	v_mfma_f32_16x16x32_bf16 v[24:27], v[232:235], v[192:195], v[24:27]
	v_mfma_f32_16x16x32_bf16 v[20:23], v[224:227], v[200:203], v[20:23]
	v_mfma_f32_16x16x32_bf16 v[16:19], v[232:235], v[200:203], v[16:19]
	v_mfma_f32_16x16x32_bf16 v[12:15], v[224:227], v[208:211], v[12:15]
	v_mfma_f32_16x16x32_bf16 v[8:11], v[232:235], v[208:211], v[8:11]
	v_mfma_f32_16x16x32_bf16 v[4:7], v[224:227], v[216:219], v[4:7]
	v_mfma_f32_16x16x32_bf16 v[0:3], v[232:235], v[216:219], v[0:3]
	v_mfma_f32_16x16x32_bf16 v[28:31], v[228:231], v[196:199], v[28:31]
	v_mfma_f32_16x16x32_bf16 v[24:27], v[236:239], v[196:199], v[24:27]
	v_mfma_f32_16x16x32_bf16 v[20:23], v[228:231], v[204:207], v[20:23]
	v_mfma_f32_16x16x32_bf16 v[16:19], v[236:239], v[204:207], v[16:19]
	v_mfma_f32_16x16x32_bf16 v[12:15], v[228:231], v[212:215], v[12:15]
	v_mfma_f32_16x16x32_bf16 v[8:11], v[236:239], v[212:215], v[8:11]
	v_mfma_f32_16x16x32_bf16 v[4:7], v[228:231], v[220:223], v[4:7]
	v_mfma_f32_16x16x32_bf16 v[0:3], v[236:239], v[220:223], v[0:3]
	s_barrier
	ds_read_b128 v[176:179], v161
	ds_read_b128 v[180:183], v161 offset:1024
	ds_read_b128 v[184:187], v161 offset:2048
	ds_read_b128 v[188:191], v161 offset:3072
	v_readfirstlane_b32 s12, v159
	v_lshl_add_u64 v[224:225], v[240:241], 0, s[30:31]
	s_mov_b32 m0, s12
	v_readfirstlane_b32 s12, v160
	ds_read_b128 v[192:195], v153 offset:32768
	ds_read_b128 v[196:199], v153 offset:33792
	ds_read_b128 v[200:203], v152 offset:32768
	ds_read_b128 v[204:207], v152 offset:33792
	ds_read_b128 v[208:211], v151 offset:32768
	ds_read_b128 v[212:215], v151 offset:33792
	ds_read_b128 v[216:219], v150 offset:32768
	ds_read_b128 v[220:223], v150 offset:33792
	global_load_lds_dwordx4 v[224:225], off
	v_lshl_add_u64 v[224:225], v[242:243], 0, s[30:31]
	s_mov_b32 m0, s12
	s_nop 0
	global_load_lds_dwordx4 v[224:225], off
	s_waitcnt lgkmcnt(8)
	s_barrier
	s_waitcnt lgkmcnt(0)
	s_waitcnt lgkmcnt(0)
	v_mfma_f32_16x16x32_bf16 v[124:127], v[176:179], v[192:195], v[124:127]
	v_mfma_f32_16x16x32_bf16 v[120:123], v[184:187], v[192:195], v[120:123]
	v_mfma_f32_16x16x32_bf16 v[116:119], v[176:179], v[200:203], v[116:119]
	v_mfma_f32_16x16x32_bf16 v[112:115], v[184:187], v[200:203], v[112:115]
	v_mfma_f32_16x16x32_bf16 v[108:111], v[176:179], v[208:211], v[108:111]
	v_mfma_f32_16x16x32_bf16 v[104:107], v[184:187], v[208:211], v[104:107]
	v_mfma_f32_16x16x32_bf16 v[100:103], v[176:179], v[216:219], v[100:103]
	v_mfma_f32_16x16x32_bf16 v[96:99], v[184:187], v[216:219], v[96:99]
	v_mfma_f32_16x16x32_bf16 v[124:127], v[180:183], v[196:199], v[124:127]
	v_mfma_f32_16x16x32_bf16 v[120:123], v[188:191], v[196:199], v[120:123]
	v_mfma_f32_16x16x32_bf16 v[116:119], v[180:183], v[204:207], v[116:119]
	v_mfma_f32_16x16x32_bf16 v[112:115], v[188:191], v[204:207], v[112:115]
	v_mfma_f32_16x16x32_bf16 v[108:111], v[180:183], v[212:215], v[108:111]
	v_mfma_f32_16x16x32_bf16 v[104:107], v[188:191], v[212:215], v[104:107]
	v_mfma_f32_16x16x32_bf16 v[100:103], v[180:183], v[220:223], v[100:103]
	v_mfma_f32_16x16x32_bf16 v[96:99], v[188:191], v[220:223], v[96:99]
	s_barrier
	v_readfirstlane_b32 s12, v162
	v_lshl_add_u64 v[244:245], v[244:245], 0, s[34:35]
	s_mov_b32 m0, s12
	v_readfirstlane_b32 s12, v163
	ds_read_b128 v[224:227], v156
	ds_read_b128 v[228:231], v156 offset:1024
	ds_read_b128 v[232:235], v156 offset:2048
	ds_read_b128 v[236:239], v156 offset:3072
	global_load_lds_dwordx4 v[244:245], off
	v_lshl_add_u64 v[244:245], v[246:247], 0, s[34:35]
	s_mov_b32 m0, s12
	s_nop 0
	global_load_lds_dwordx4 v[244:245], off
	s_barrier
	s_waitcnt lgkmcnt(0)
	s_waitcnt lgkmcnt(0)
	v_mfma_f32_16x16x32_bf16 v[92:95], v[224:227], v[192:195], v[92:95]
	v_mfma_f32_16x16x32_bf16 v[88:91], v[232:235], v[192:195], v[88:91]
	v_mfma_f32_16x16x32_bf16 v[84:87], v[224:227], v[200:203], v[84:87]
	v_mfma_f32_16x16x32_bf16 v[80:83], v[232:235], v[200:203], v[80:83]
	v_mfma_f32_16x16x32_bf16 v[76:79], v[224:227], v[208:211], v[76:79]
	v_mfma_f32_16x16x32_bf16 v[72:75], v[232:235], v[208:211], v[72:75]
	v_mfma_f32_16x16x32_bf16 v[68:71], v[224:227], v[216:219], v[68:71]
	v_mfma_f32_16x16x32_bf16 v[64:67], v[232:235], v[216:219], v[64:67]
	v_mfma_f32_16x16x32_bf16 v[92:95], v[228:231], v[196:199], v[92:95]
	v_mfma_f32_16x16x32_bf16 v[88:91], v[236:239], v[196:199], v[88:91]
	v_mfma_f32_16x16x32_bf16 v[84:87], v[228:231], v[204:207], v[84:87]
	v_mfma_f32_16x16x32_bf16 v[80:83], v[236:239], v[204:207], v[80:83]
	v_mfma_f32_16x16x32_bf16 v[76:79], v[228:231], v[212:215], v[76:79]
	v_mfma_f32_16x16x32_bf16 v[72:75], v[236:239], v[212:215], v[72:75]
	v_mfma_f32_16x16x32_bf16 v[68:71], v[228:231], v[220:223], v[68:71]
	v_mfma_f32_16x16x32_bf16 v[64:67], v[236:239], v[220:223], v[64:67]
	v_readfirstlane_b32 s12, v164
	v_lshl_add_u64 v[240:241], v[240:241], 0, s[34:35]
	s_mov_b32 m0, s12
	v_readfirstlane_b32 s12, v165
	s_barrier
	ds_read_b128 v[192:195], v153 offset:49152
	ds_read_b128 v[196:199], v153 offset:50176
	ds_read_b128 v[200:203], v152 offset:49152
	ds_read_b128 v[204:207], v152 offset:50176
	ds_read_b128 v[208:211], v151 offset:49152
	ds_read_b128 v[212:215], v151 offset:50176
	ds_read_b128 v[216:219], v150 offset:49152
	ds_read_b128 v[220:223], v150 offset:50176
	global_load_lds_dwordx4 v[240:241], off
	v_lshl_add_u64 v[240:241], v[242:243], 0, s[34:35]
	s_mov_b32 m0, s12
	s_nop 0
	global_load_lds_dwordx4 v[240:241], off
	s_barrier
; #define WAIT_V(n) asm volatile("s_waitcnt vmcnt(" #n ")" ::: "memory")
; #define WAIT_L(n) asm volatile("s_waitcnt lgkmcnt(" #n ")" ::: "memory")
; #define BAR __builtin_amdgcn_s_barrier()
; #define SCHED __builtin_amdgcn_sched_barrier(0)
;     ...
;     BAR; WAIT_L(0); MMA(1, 0, At, B0); BAR; SCHED;
;     STAGE(SB(1, 1), Bt, bcol1, t + 3);
;     WAIT_V(6); BAR; MMA(1, 1, At, B1); BAR;
;   }
;   { LDB(B0, 0, 0); LDA(At, 0, 0); STAGE(SA(1, 1), A, brow + HALF, nt - 1);
;     BAR; WAIT_L(0); MMA(0, 0, At, B0); BAR;
;     LDB(B1, 0, 1); BAR; WAIT_L(0); MMA(0, 1, At, B1); BAR;
	s_waitcnt lgkmcnt(0)
	s_waitcnt lgkmcnt(0)
	v_mfma_f32_16x16x32_bf16 v[60:63], v[176:179], v[192:195], v[60:63]
	v_mfma_f32_16x16x32_bf16 v[56:59], v[184:187], v[192:195], v[56:59]
	v_mfma_f32_16x16x32_bf16 v[52:55], v[176:179], v[200:203], v[52:55]
	v_mfma_f32_16x16x32_bf16 v[48:51], v[184:187], v[200:203], v[48:51]
	v_mfma_f32_16x16x32_bf16 v[44:47], v[176:179], v[208:211], v[44:47]
	v_mfma_f32_16x16x32_bf16 v[40:43], v[184:187], v[208:211], v[40:43]
	v_mfma_f32_16x16x32_bf16 v[36:39], v[176:179], v[216:219], v[36:39]
	v_mfma_f32_16x16x32_bf16 v[32:35], v[184:187], v[216:219], v[32:35]
	v_mfma_f32_16x16x32_bf16 v[60:63], v[180:183], v[196:199], v[60:63]
	v_mfma_f32_16x16x32_bf16 v[56:59], v[188:191], v[196:199], v[56:59]
	v_mfma_f32_16x16x32_bf16 v[52:55], v[180:183], v[204:207], v[52:55]
	v_mfma_f32_16x16x32_bf16 v[48:51], v[188:191], v[204:207], v[48:51]
	v_mfma_f32_16x16x32_bf16 v[44:47], v[180:183], v[212:215], v[44:47]
	v_mfma_f32_16x16x32_bf16 v[40:43], v[188:191], v[212:215], v[40:43]
	v_mfma_f32_16x16x32_bf16 v[36:39], v[180:183], v[220:223], v[36:39]
	v_mfma_f32_16x16x32_bf16 v[32:35], v[188:191], v[220:223], v[32:35]
	s_barrier
	v_readfirstlane_b32 s12, v168
	v_lshl_add_u64 v[176:177], v[248:249], 0, s[36:37]
	s_mov_b32 m0, s12
	v_readfirstlane_b32 s12, v171
	global_load_lds_dwordx4 v[176:177], off
	v_lshl_add_u64 v[176:177], v[250:251], 0, s[36:37]
	s_mov_b32 m0, s12
	s_nop 0
	global_load_lds_dwordx4 v[176:177], off
	s_waitcnt vmcnt(6)
	s_barrier
	v_mfma_f32_16x16x32_bf16 v[28:31], v[224:227], v[192:195], v[28:31]
	v_mfma_f32_16x16x32_bf16 v[24:27], v[232:235], v[192:195], v[24:27]
	v_mfma_f32_16x16x32_bf16 v[20:23], v[224:227], v[200:203], v[20:23]
	v_mfma_f32_16x16x32_bf16 v[16:19], v[232:235], v[200:203], v[16:19]
	v_mfma_f32_16x16x32_bf16 v[12:15], v[224:227], v[208:211], v[12:15]
	v_mfma_f32_16x16x32_bf16 v[8:11], v[232:235], v[208:211], v[8:11]
	v_mfma_f32_16x16x32_bf16 v[4:7], v[224:227], v[216:219], v[4:7]
	v_mfma_f32_16x16x32_bf16 v[0:3], v[232:235], v[216:219], v[0:3]
	v_mfma_f32_16x16x32_bf16 v[28:31], v[228:231], v[196:199], v[28:31]
	v_mfma_f32_16x16x32_bf16 v[24:27], v[236:239], v[196:199], v[24:27]
	v_mfma_f32_16x16x32_bf16 v[20:23], v[228:231], v[204:207], v[20:23]
	v_mfma_f32_16x16x32_bf16 v[16:19], v[236:239], v[204:207], v[16:19]
	v_mfma_f32_16x16x32_bf16 v[12:15], v[228:231], v[212:215], v[12:15]
	v_mfma_f32_16x16x32_bf16 v[8:11], v[236:239], v[212:215], v[8:11]
	v_mfma_f32_16x16x32_bf16 v[4:7], v[228:231], v[220:223], v[4:7]
	v_mfma_f32_16x16x32_bf16 v[0:3], v[236:239], v[220:223], v[0:3]
	s_add_i32 s7, s7, 2
	s_add_u32 s4, s4, 0x100
	s_addc_u32 s5, s5, 0
	s_cmp_lt_u32 s7, 60
	s_barrier
	s_cbranch_scc1 .LBB0_1236
	s_add_u32 s4, s8, 0x1f80
	s_addc_u32 s5, s9, 0
	v_readfirstlane_b32 s7, v174
	v_lshl_add_u64 v[142:143], s[4:5], 0, v[148:149]
	s_mov_b32 m0, s7
	v_lshl_add_u64 v[128:129], s[4:5], 0, v[128:129]
	v_readfirstlane_b32 s4, v175
	ds_read_b128 v[130:133], v173
	ds_read_b128 v[134:137], v173 offset:1024
	ds_read_b128 v[138:141], v173 offset:2048
	ds_read_b128 v[162:165], v173 offset:3072
	ds_read_b128 v[176:179], v153
	ds_read_b128 v[180:183], v153 offset:1024
	ds_read_b128 v[184:187], v152
	ds_read_b128 v[188:191], v152 offset:1024
	ds_read_b128 v[192:195], v151
	ds_read_b128 v[196:199], v151 offset:1024
	ds_read_b128 v[200:203], v150
	ds_read_b128 v[204:207], v150 offset:1024
	global_load_lds_dwordx4 v[142:143], off
	s_mov_b32 m0, s4
	s_nop 0
	global_load_lds_dwordx4 v[128:129], off
	s_barrier
	s_waitcnt lgkmcnt(0)
	s_waitcnt lgkmcnt(0)
	v_mfma_f32_16x16x32_bf16 v[116:119], v[130:133], v[184:187], v[116:119]
	v_mfma_f32_16x16x32_bf16 v[108:111], v[130:133], v[192:195], v[108:111]
	v_mfma_f32_16x16x32_bf16 v[100:103], v[130:133], v[200:203], v[100:103]
	v_mfma_f32_16x16x32_bf16 v[96:99], v[138:141], v[200:203], v[96:99]
	v_mfma_f32_16x16x32_bf16 v[124:127], v[130:133], v[176:179], v[124:127]
	v_mfma_f32_16x16x32_bf16 v[120:123], v[138:141], v[176:179], v[120:123]
	v_mfma_f32_16x16x32_bf16 v[116:119], v[134:137], v[188:191], v[116:119]
	v_mfma_f32_16x16x32_bf16 v[112:115], v[138:141], v[184:187], v[112:115]
	v_mfma_f32_16x16x32_bf16 v[108:111], v[134:137], v[196:199], v[108:111]
	v_mfma_f32_16x16x32_bf16 v[104:107], v[138:141], v[192:195], v[104:107]
	v_mfma_f32_16x16x32_bf16 v[100:103], v[134:137], v[204:207], v[100:103]
	v_mfma_f32_16x16x32_bf16 v[96:99], v[162:165], v[204:207], v[96:99]
	v_mfma_f32_16x16x32_bf16 v[124:127], v[134:137], v[180:183], v[124:127]
	v_mfma_f32_16x16x32_bf16 v[208:211], v[162:165], v[180:183], v[120:123]
	v_mfma_f32_16x16x32_bf16 v[212:215], v[162:165], v[188:191], v[112:115]
	v_mfma_f32_16x16x32_bf16 v[216:219], v[162:165], v[196:199], v[104:107]
	s_barrier
	s_nop 0
	ds_read_b128 v[104:107], v172
	ds_read_b128 v[112:115], v172 offset:1024
	ds_read_b128 v[120:123], v172 offset:2048
	ds_read_b128 v[172:175], v172 offset:3072
	s_barrier
	s_waitcnt lgkmcnt(0)
	s_waitcnt lgkmcnt(0)
	v_mfma_f32_16x16x32_bf16 v[92:95], v[104:107], v[176:179], v[92:95]
	v_mfma_f32_16x16x32_bf16 v[84:87], v[104:107], v[184:187], v[84:87]
	v_mfma_f32_16x16x32_bf16 v[76:79], v[104:107], v[192:195], v[76:79]
	v_mfma_f32_16x16x32_bf16 v[64:67], v[120:123], v[200:203], v[64:67]
	v_mfma_f32_16x16x32_bf16 v[92:95], v[112:115], v[180:183], v[92:95]
	v_mfma_f32_16x16x32_bf16 v[88:91], v[120:123], v[176:179], v[88:91]
	v_mfma_f32_16x16x32_bf16 v[84:87], v[112:115], v[188:191], v[84:87]
	v_mfma_f32_16x16x32_bf16 v[80:83], v[120:123], v[184:187], v[80:83]
	v_mfma_f32_16x16x32_bf16 v[76:79], v[112:115], v[196:199], v[76:79]
	v_mfma_f32_16x16x32_bf16 v[72:75], v[120:123], v[192:195], v[72:75]
	v_mfma_f32_16x16x32_bf16 v[68:71], v[104:107], v[200:203], v[68:71]
	v_mfma_f32_16x16x32_bf16 v[64:67], v[172:175], v[204:207], v[64:67]
	v_mfma_f32_16x16x32_bf16 v[176:179], v[172:175], v[180:183], v[88:91]
	v_mfma_f32_16x16x32_bf16 v[180:183], v[172:175], v[188:191], v[80:83]
	v_mfma_f32_16x16x32_bf16 v[184:187], v[172:175], v[196:199], v[72:75]
	v_mfma_f32_16x16x32_bf16 v[188:191], v[112:115], v[204:207], v[68:71]
	s_barrier
; #define WAIT_V(n) asm volatile("s_waitcnt vmcnt(" #n ")" ::: "memory")
; #define WAIT_L(n) asm volatile("s_waitcnt lgkmcnt(" #n ")" ::: "memory")
; #define BAR __builtin_amdgcn_s_barrier()
;     ...
;     LDA(At, 0, 1); WAIT_V(4); BAR; WAIT_L(0); MMA(1, 0, At, B0); MMA(1, 1, At, B1); BAR; }
;   { LDB(B0, 1, 0); LDA(At, 1, 0); WAIT_V(2); BAR; WAIT_L(0); MMA(0, 0, At, B0); BAR;
	s_nop 0
	ds_read_b128 v[68:71], v153 offset:16384
	ds_read_b128 v[72:75], v153 offset:17408
	ds_read_b128 v[80:83], v152 offset:16384
	ds_read_b128 v[88:91], v152 offset:17408
	ds_read_b128 v[192:195], v151 offset:16384
	ds_read_b128 v[196:199], v151 offset:17408
	ds_read_b128 v[200:203], v150 offset:16384
	ds_read_b128 v[204:207], v150 offset:17408
	s_waitcnt vmcnt(4)
	s_barrier
	s_waitcnt lgkmcnt(0)
	s_waitcnt lgkmcnt(0)
	v_mfma_f32_16x16x32_bf16 v[60:63], v[130:133], v[68:71], v[60:63]
	v_mfma_f32_16x16x32_bf16 v[52:55], v[130:133], v[80:83], v[52:55]
	v_mfma_f32_16x16x32_bf16 v[44:47], v[130:133], v[192:195], v[44:47]
	v_mfma_f32_16x16x32_bf16 v[36:39], v[130:133], v[200:203], v[36:39]
	v_mfma_f32_16x16x32_bf16 v[32:35], v[138:141], v[200:203], v[32:35]
	v_mfma_f32_16x16x32_bf16 v[60:63], v[134:137], v[72:75], v[60:63]
	v_mfma_f32_16x16x32_bf16 v[56:59], v[138:141], v[68:71], v[56:59]
	v_mfma_f32_16x16x32_bf16 v[52:55], v[134:137], v[88:91], v[52:55]
	v_mfma_f32_16x16x32_bf16 v[48:51], v[138:141], v[80:83], v[48:51]
	v_mfma_f32_16x16x32_bf16 v[44:47], v[134:137], v[196:199], v[44:47]
	v_mfma_f32_16x16x32_bf16 v[40:43], v[138:141], v[192:195], v[40:43]
	v_mfma_f32_16x16x32_bf16 v[36:39], v[134:137], v[204:207], v[36:39]
	v_mfma_f32_16x16x32_bf16 v[32:35], v[162:165], v[204:207], v[32:35]
	v_mfma_f32_16x16x32_bf16 v[220:223], v[162:165], v[72:75], v[56:59]
	v_mfma_f32_16x16x32_bf16 v[224:227], v[162:165], v[88:91], v[48:51]
	v_mfma_f32_16x16x32_bf16 v[228:231], v[162:165], v[196:199], v[40:43]
	v_mfma_f32_16x16x32_bf16 v[28:31], v[104:107], v[68:71], v[28:31]
	v_mfma_f32_16x16x32_bf16 v[20:23], v[104:107], v[80:83], v[20:23]
	v_mfma_f32_16x16x32_bf16 v[12:15], v[104:107], v[192:195], v[12:15]
	v_mfma_f32_16x16x32_bf16 v[0:3], v[120:123], v[200:203], v[0:3]
	v_mfma_f32_16x16x32_bf16 v[28:31], v[112:115], v[72:75], v[28:31]
	v_mfma_f32_16x16x32_bf16 v[24:27], v[120:123], v[68:71], v[24:27]
	v_mfma_f32_16x16x32_bf16 v[20:23], v[112:115], v[88:91], v[20:23]
	v_mfma_f32_16x16x32_bf16 v[16:19], v[120:123], v[80:83], v[16:19]
	v_mfma_f32_16x16x32_bf16 v[12:15], v[112:115], v[196:199], v[12:15]
	v_mfma_f32_16x16x32_bf16 v[8:11], v[120:123], v[192:195], v[8:11]
	v_mfma_f32_16x16x32_bf16 v[4:7], v[104:107], v[200:203], v[4:7]
	v_mfma_f32_16x16x32_bf16 v[0:3], v[172:175], v[204:207], v[0:3]
	v_mfma_f32_16x16x32_bf16 v[128:131], v[172:175], v[72:75], v[24:27]
	v_mfma_f32_16x16x32_bf16 v[132:135], v[172:175], v[88:91], v[16:19]
	v_mfma_f32_16x16x32_bf16 v[136:139], v[172:175], v[196:199], v[8:11]
	v_mfma_f32_16x16x32_bf16 v[162:165], v[112:115], v[204:207], v[4:7]
	s_barrier
	s_nop 0
	ds_read_b128 v[4:7], v161
	ds_read_b128 v[172:175], v161 offset:1024
	ds_read_b128 v[192:195], v161 offset:2048
	ds_read_b128 v[158:161], v161 offset:3072
	ds_read_b128 v[8:11], v153 offset:32768
	ds_read_b128 v[16:19], v153 offset:33792
	ds_read_b128 v[24:27], v152 offset:32768
	ds_read_b128 v[40:43], v152 offset:33792
	ds_read_b128 v[48:51], v151 offset:32768
	ds_read_b128 v[56:59], v151 offset:33792
	ds_read_b128 v[196:199], v150 offset:32768
	ds_read_b128 v[200:203], v150 offset:33792
	s_waitcnt vmcnt(2)
	s_barrier
	s_waitcnt lgkmcnt(0)
	s_waitcnt lgkmcnt(0)
	v_mfma_f32_16x16x32_bf16 v[68:71], v[4:7], v[8:11], v[124:127]
	v_mfma_f32_16x16x32_bf16 v[120:123], v[172:175], v[16:19], v[68:71]
	v_mfma_f32_16x16x32_bf16 v[68:71], v[192:195], v[8:11], v[208:211]
	v_mfma_f32_16x16x32_bf16 v[88:91], v[158:161], v[16:19], v[68:71]
	v_mfma_f32_16x16x32_bf16 v[68:71], v[4:7], v[24:27], v[116:119]
	v_mfma_f32_16x16x32_bf16 v[112:115], v[172:175], v[40:43], v[68:71]
	v_mfma_f32_16x16x32_bf16 v[68:71], v[192:195], v[24:27], v[212:215]
	v_mfma_f32_16x16x32_bf16 v[80:83], v[158:161], v[40:43], v[68:71]
	v_mfma_f32_16x16x32_bf16 v[68:71], v[4:7], v[48:51], v[108:111]
	v_mfma_f32_16x16x32_bf16 v[104:107], v[172:175], v[56:59], v[68:71]
	v_mfma_f32_16x16x32_bf16 v[68:71], v[192:195], v[48:51], v[216:219]
	v_mfma_f32_16x16x32_bf16 v[72:75], v[158:161], v[56:59], v[68:71]
	v_mfma_f32_16x16x32_bf16 v[68:71], v[4:7], v[196:199], v[100:103]
	v_mfma_f32_16x16x32_bf16 v[100:103], v[172:175], v[200:203], v[68:71]
	v_mfma_f32_16x16x32_bf16 v[68:71], v[192:195], v[196:199], v[96:99]
	v_mfma_f32_16x16x32_bf16 v[68:71], v[158:161], v[200:203], v[68:71]
	s_barrier
; #define WAIT_V(n) asm volatile("s_waitcnt vmcnt(" #n ")" ::: "memory")
; #define WAIT_L(n) asm volatile("s_waitcnt lgkmcnt(" #n ")" ::: "memory")
; #define BAR __builtin_amdgcn_s_barrier()
;     ...
;     LDB(B1, 1, 1); WAIT_V(0); BAR; WAIT_L(0); MMA(0, 1, At, B1); BAR;
;     LDA(At, 1, 1); BAR; WAIT_L(0); MMA(1, 0, At, B0); MMA(1, 1, At, B1); BAR; }
;   if (wr == 0) BAR;
	ds_read_b128 v[124:127], v156
	ds_read_b128 v[204:207], v156 offset:1024
	ds_read_b128 v[208:211], v156 offset:2048
	ds_read_b128 v[154:157], v156 offset:3072
	s_waitcnt vmcnt(0)
	s_barrier
	s_waitcnt lgkmcnt(0)
	s_waitcnt lgkmcnt(0)
	v_mfma_f32_16x16x32_bf16 v[92:95], v[124:127], v[8:11], v[92:95]
	v_mfma_f32_16x16x32_bf16 v[8:11], v[208:211], v[8:11], v[176:179]
	v_mfma_f32_16x16x32_bf16 v[140:143], v[204:207], v[16:19], v[92:95]
	v_mfma_f32_16x16x32_bf16 v[92:95], v[154:157], v[16:19], v[8:11]
	v_mfma_f32_16x16x32_bf16 v[8:11], v[124:127], v[24:27], v[84:87]
	v_mfma_f32_16x16x32_bf16 v[116:119], v[204:207], v[40:43], v[8:11]
	v_mfma_f32_16x16x32_bf16 v[8:11], v[208:211], v[24:27], v[180:183]
	v_mfma_f32_16x16x32_bf16 v[84:87], v[154:157], v[40:43], v[8:11]
	v_mfma_f32_16x16x32_bf16 v[8:11], v[124:127], v[48:51], v[76:79]
	v_mfma_f32_16x16x32_bf16 v[108:111], v[204:207], v[56:59], v[8:11]
	v_mfma_f32_16x16x32_bf16 v[8:11], v[208:211], v[48:51], v[184:187]
	v_mfma_f32_16x16x32_bf16 v[76:79], v[154:157], v[56:59], v[8:11]
	v_mfma_f32_16x16x32_bf16 v[8:11], v[124:127], v[196:199], v[188:191]
	v_mfma_f32_16x16x32_bf16 v[96:99], v[204:207], v[200:203], v[8:11]
	v_mfma_f32_16x16x32_bf16 v[8:11], v[208:211], v[196:199], v[64:67]
	v_mfma_f32_16x16x32_bf16 v[64:67], v[154:157], v[200:203], v[8:11]
	s_barrier
	ds_read_b128 v[176:179], v153 offset:49152
	ds_read_b128 v[180:183], v153 offset:50176
	ds_read_b128 v[184:187], v152 offset:49152
	ds_read_b128 v[188:191], v152 offset:50176
	ds_read_b128 v[196:199], v151 offset:49152
	ds_read_b128 v[200:203], v151 offset:50176
	ds_read_b128 v[212:215], v150 offset:49152
	ds_read_b128 v[150:153], v150 offset:50176
	s_barrier
	s_waitcnt lgkmcnt(0)
	s_waitcnt lgkmcnt(0)
	v_mfma_f32_16x16x32_bf16 v[8:11], v[4:7], v[176:179], v[60:63]
	v_mfma_f32_16x16x32_bf16 v[56:59], v[172:175], v[180:183], v[8:11]
	v_mfma_f32_16x16x32_bf16 v[8:11], v[192:195], v[176:179], v[220:223]
	v_mfma_f32_16x16x32_bf16 v[24:27], v[158:161], v[180:183], v[8:11]
	v_mfma_f32_16x16x32_bf16 v[8:11], v[4:7], v[184:187], v[52:55]
	v_mfma_f32_16x16x32_bf16 v[48:51], v[172:175], v[188:191], v[8:11]
	v_mfma_f32_16x16x32_bf16 v[8:11], v[192:195], v[184:187], v[224:227]
	v_mfma_f32_16x16x32_bf16 v[16:19], v[158:161], v[188:191], v[8:11]
	v_mfma_f32_16x16x32_bf16 v[8:11], v[4:7], v[196:199], v[44:47]
	v_mfma_f32_16x16x32_bf16 v[4:7], v[4:7], v[212:215], v[36:39]
	v_mfma_f32_16x16x32_bf16 v[40:43], v[172:175], v[200:203], v[8:11]
	v_mfma_f32_16x16x32_bf16 v[8:11], v[192:195], v[196:199], v[228:231]
	v_mfma_f32_16x16x32_bf16 v[36:39], v[172:175], v[150:153], v[4:7]
	v_mfma_f32_16x16x32_bf16 v[4:7], v[192:195], v[212:215], v[32:35]
	v_mfma_f32_16x16x32_bf16 v[8:11], v[158:161], v[200:203], v[8:11]
	v_mfma_f32_16x16x32_bf16 v[4:7], v[158:161], v[150:153], v[4:7]
	v_mfma_f32_16x16x32_bf16 v[28:31], v[124:127], v[176:179], v[28:31]
	v_mfma_f32_16x16x32_bf16 v[20:23], v[124:127], v[184:187], v[20:23]
	v_mfma_f32_16x16x32_bf16 v[12:15], v[124:127], v[196:199], v[12:15]
	v_mfma_f32_16x16x32_bf16 v[60:63], v[204:207], v[180:183], v[28:31]
	v_mfma_f32_16x16x32_bf16 v[28:31], v[208:211], v[176:179], v[128:131]
	v_mfma_f32_16x16x32_bf16 v[52:55], v[204:207], v[188:191], v[20:23]
	v_mfma_f32_16x16x32_bf16 v[20:23], v[208:211], v[184:187], v[132:135]
	v_mfma_f32_16x16x32_bf16 v[44:47], v[204:207], v[200:203], v[12:15]
	v_mfma_f32_16x16x32_bf16 v[12:15], v[208:211], v[196:199], v[136:139]
	v_mfma_f32_16x16x32_bf16 v[32:35], v[124:127], v[212:215], v[162:165]
	v_mfma_f32_16x16x32_bf16 v[0:3], v[208:211], v[212:215], v[0:3]
	v_mfma_f32_16x16x32_bf16 v[28:31], v[154:157], v[180:183], v[28:31]
	v_mfma_f32_16x16x32_bf16 v[20:23], v[154:157], v[188:191], v[20:23]
	v_mfma_f32_16x16x32_bf16 v[12:15], v[154:157], v[200:203], v[12:15]
	v_mfma_f32_16x16x32_bf16 v[32:35], v[204:207], v[150:153], v[32:35]
	v_mfma_f32_16x16x32_bf16 v[0:3], v[154:157], v[150:153], v[0:3]
	v_cmp_gt_u32_e64 s[4:5], s84, v145
	s_barrier
	s_and_saveexec_b64 s[8:9], s[4:5]
	s_cbranch_execz .LBB0_1239
	s_barrier

; #define WAIT_L(n) asm volatile("s_waitcnt lgkmcnt(" #n ")" ::: "memory")
; #define BAR __builtin_amdgcn_s_barrier()
; #define SCHED __builtin_amdgcn_sched_barrier(0)
;     ...
;   for (int t = 0; t < nt - 2; t += 2) {
;     LDB(B0, 0, 0); SCHED; LDA(At, 0, 0); STAGE(SA(1, 1), A, brow + HALF, t + 1);
;     WAIT_L(8); BAR; WAIT_L(0); MMA(0, 0, At, B0); BAR; SCHED;
;     LDB(B1, 0, 1); STAGE(SB(0, 0), Bt, bcol, t + 2);
;     BAR; WAIT_L(0); MMA(0, 1, At, B1); BAR;
;     LDA(At, 0, 1); STAGE(SA(0, 0), A, brow, t + 2);
;     BAR; WAIT_L(0); MMA(1, 0, At, B0); BAR; SCHED;
.LBB0_1335:
	ds_read_b128 v[172:175], v169
	ds_read_b128 v[176:179], v169 offset:1024
	ds_read_b128 v[180:183], v169 offset:2048
	ds_read_b128 v[184:187], v169 offset:3072
	v_add_u32_e32 v170, 0xc000, v155
	v_lshl_add_u64 v[236:237], v[136:137], 0, s[6:7]
	v_readfirstlane_b32 s23, v170
	v_add_u32_e32 v171, 0xe000, v155
	v_lshl_add_u64 v[220:221], v[236:237], 0, s[12:13]
	s_mov_b32 m0, s23
	v_lshl_add_u64 v[238:239], v[138:139], 0, s[6:7]
	v_readfirstlane_b32 s23, v171
	ds_read_b128 v[188:191], v151
	ds_read_b128 v[192:195], v151 offset:1024
	ds_read_b128 v[196:199], v150
	ds_read_b128 v[200:203], v150 offset:1024
	ds_read_b128 v[204:207], v145
	ds_read_b128 v[208:211], v145 offset:1024
	ds_read_b128 v[212:215], v144
	ds_read_b128 v[216:219], v144 offset:1024
	global_load_lds_dwordx4 v[220:221], off
	v_lshl_add_u64 v[220:221], v[238:239], 0, s[12:13]
	s_mov_b32 m0, s23
	s_nop 0
	global_load_lds_dwordx4 v[220:221], off
	s_waitcnt lgkmcnt(8)
	s_barrier
	s_waitcnt lgkmcnt(0)
	s_waitcnt lgkmcnt(0)
	v_mfma_f32_16x16x32_bf16 v[124:127], v[172:175], v[188:191], v[124:127]
	v_mfma_f32_16x16x32_bf16 v[120:123], v[180:183], v[188:191], v[120:123]
	v_mfma_f32_16x16x32_bf16 v[116:119], v[172:175], v[196:199], v[116:119]
	v_mfma_f32_16x16x32_bf16 v[112:115], v[180:183], v[196:199], v[112:115]
	v_mfma_f32_16x16x32_bf16 v[108:111], v[172:175], v[204:207], v[108:111]
	v_mfma_f32_16x16x32_bf16 v[104:107], v[180:183], v[204:207], v[104:107]
	v_mfma_f32_16x16x32_bf16 v[100:103], v[172:175], v[212:215], v[100:103]
	v_mfma_f32_16x16x32_bf16 v[96:99], v[180:183], v[212:215], v[96:99]
	v_mfma_f32_16x16x32_bf16 v[124:127], v[176:179], v[192:195], v[124:127]
	v_mfma_f32_16x16x32_bf16 v[120:123], v[184:187], v[192:195], v[120:123]
	v_mfma_f32_16x16x32_bf16 v[116:119], v[176:179], v[200:203], v[116:119]
	v_mfma_f32_16x16x32_bf16 v[112:115], v[184:187], v[200:203], v[112:115]
	v_mfma_f32_16x16x32_bf16 v[108:111], v[176:179], v[208:211], v[108:111]
	v_mfma_f32_16x16x32_bf16 v[104:107], v[184:187], v[208:211], v[104:107]
	v_mfma_f32_16x16x32_bf16 v[100:103], v[176:179], v[216:219], v[100:103]
	v_mfma_f32_16x16x32_bf16 v[96:99], v[184:187], v[216:219], v[96:99]
	s_barrier
	v_lshl_add_u64 v[240:241], v[132:133], 0, s[6:7]
	v_readfirstlane_b32 s23, v152
	v_lshl_add_u64 v[242:243], v[240:241], 0, s[14:15]
	s_mov_b32 m0, s23
	ds_read_b128 v[220:223], v168
	ds_read_b128 v[224:227], v168 offset:1024
	ds_read_b128 v[228:231], v168 offset:2048
	ds_read_b128 v[232:235], v168 offset:3072
	global_load_lds_dwordx4 v[242:243], off
	v_lshl_add_u64 v[242:243], v[134:135], 0, s[6:7]
	v_readfirstlane_b32 s23, v153
	v_lshl_add_u64 v[244:245], v[242:243], 0, s[14:15]
	s_mov_b32 m0, s23
	s_nop 0
	global_load_lds_dwordx4 v[244:245], off
	s_barrier
	s_waitcnt lgkmcnt(0)
	s_waitcnt lgkmcnt(0)
	v_mfma_f32_16x16x32_bf16 v[92:95], v[220:223], v[188:191], v[92:95]
	v_mfma_f32_16x16x32_bf16 v[88:91], v[228:231], v[188:191], v[88:91]
	v_mfma_f32_16x16x32_bf16 v[84:87], v[220:223], v[196:199], v[84:87]
	v_mfma_f32_16x16x32_bf16 v[80:83], v[228:231], v[196:199], v[80:83]
	v_mfma_f32_16x16x32_bf16 v[76:79], v[220:223], v[204:207], v[76:79]
	v_mfma_f32_16x16x32_bf16 v[72:75], v[228:231], v[204:207], v[72:75]
	v_mfma_f32_16x16x32_bf16 v[68:71], v[220:223], v[212:215], v[68:71]
	v_mfma_f32_16x16x32_bf16 v[64:67], v[228:231], v[212:215], v[64:67]
	v_mfma_f32_16x16x32_bf16 v[92:95], v[224:227], v[192:195], v[92:95]
	v_mfma_f32_16x16x32_bf16 v[88:91], v[232:235], v[192:195], v[88:91]
	v_mfma_f32_16x16x32_bf16 v[84:87], v[224:227], v[200:203], v[84:87]
	v_mfma_f32_16x16x32_bf16 v[80:83], v[232:235], v[200:203], v[80:83]
	v_mfma_f32_16x16x32_bf16 v[76:79], v[224:227], v[208:211], v[76:79]
	v_mfma_f32_16x16x32_bf16 v[72:75], v[232:235], v[208:211], v[72:75]
	v_mfma_f32_16x16x32_bf16 v[68:71], v[224:227], v[216:219], v[68:71]
	v_mfma_f32_16x16x32_bf16 v[64:67], v[232:235], v[216:219], v[64:67]
	v_readfirstlane_b32 s23, v155
	v_lshl_add_u64 v[244:245], v[236:237], 0, s[14:15]
	s_mov_b32 m0, s23
	v_readfirstlane_b32 s23, v156
	s_barrier
	ds_read_b128 v[188:191], v151 offset:16384
	ds_read_b128 v[192:195], v151 offset:17408
	ds_read_b128 v[196:199], v150 offset:16384
	ds_read_b128 v[200:203], v150 offset:17408
	ds_read_b128 v[204:207], v145 offset:16384
	ds_read_b128 v[208:211], v145 offset:17408
	ds_read_b128 v[212:215], v144 offset:16384
	ds_read_b128 v[216:219], v144 offset:17408
	global_load_lds_dwordx4 v[244:245], off
	v_lshl_add_u64 v[244:245], v[238:239], 0, s[14:15]
	s_mov_b32 m0, s23
	s_nop 0
	global_load_lds_dwordx4 v[244:245], off
	s_barrier
	s_waitcnt lgkmcnt(0)
	s_waitcnt lgkmcnt(0)
	v_mfma_f32_16x16x32_bf16 v[60:63], v[172:175], v[188:191], v[60:63]
	v_mfma_f32_16x16x32_bf16 v[56:59], v[180:183], v[188:191], v[56:59]
	v_mfma_f32_16x16x32_bf16 v[52:55], v[172:175], v[196:199], v[52:55]
	v_mfma_f32_16x16x32_bf16 v[48:51], v[180:183], v[196:199], v[48:51]
	v_mfma_f32_16x16x32_bf16 v[44:47], v[172:175], v[204:207], v[44:47]
	v_mfma_f32_16x16x32_bf16 v[40:43], v[180:183], v[204:207], v[40:43]
	v_mfma_f32_16x16x32_bf16 v[36:39], v[172:175], v[212:215], v[36:39]
	v_mfma_f32_16x16x32_bf16 v[32:35], v[180:183], v[212:215], v[32:35]
	v_mfma_f32_16x16x32_bf16 v[60:63], v[176:179], v[192:195], v[60:63]
	v_mfma_f32_16x16x32_bf16 v[56:59], v[184:187], v[192:195], v[56:59]
	v_mfma_f32_16x16x32_bf16 v[52:55], v[176:179], v[200:203], v[52:55]
	v_mfma_f32_16x16x32_bf16 v[48:51], v[184:187], v[200:203], v[48:51]
	v_mfma_f32_16x16x32_bf16 v[44:47], v[176:179], v[208:211], v[44:47]
	v_mfma_f32_16x16x32_bf16 v[40:43], v[184:187], v[208:211], v[40:43]
	v_mfma_f32_16x16x32_bf16 v[36:39], v[176:179], v[216:219], v[36:39]
	v_mfma_f32_16x16x32_bf16 v[32:35], v[184:187], v[216:219], v[32:35]
	s_barrier
; #define WAIT_V(n) asm volatile("s_waitcnt vmcnt(" #n ")" ::: "memory")
; #define WAIT_L(n) asm volatile("s_waitcnt lgkmcnt(" #n ")" ::: "memory")
; #define BAR __builtin_amdgcn_s_barrier()
; #define SCHED __builtin_amdgcn_sched_barrier(0)
;     ...
;     STAGE(SB(0, 1), Bt, bcol1, t + 2);
;     WAIT_V(6); BAR; MMA(1, 1, At, B1); BAR;
;     LDB(B0, 1, 0); SCHED; LDA(At, 1, 0); STAGE(SA(0, 1), A, brow + HALF, t + 2);
;     WAIT_L(8); BAR; WAIT_L(0); MMA(0, 0, At, B0); BAR; SCHED;
;     LDB(B1, 1, 1); STAGE(SB(1, 0), Bt, bcol, t + 3);
;     BAR; WAIT_L(0); MMA(0, 1, At, B1); BAR;
;     LDA(At, 1, 1); STAGE(SA(1, 0), A, brow, t + 3);
	v_readfirstlane_b32 s23, v157
	v_lshl_add_u64 v[172:173], v[240:241], 0, s[16:17]
	s_mov_b32 m0, s23
	v_readfirstlane_b32 s23, v158
	global_load_lds_dwordx4 v[172:173], off
	v_lshl_add_u64 v[172:173], v[242:243], 0, s[16:17]
	s_mov_b32 m0, s23
	s_nop 0
	global_load_lds_dwordx4 v[172:173], off
	s_waitcnt vmcnt(6)
	s_barrier
	v_mfma_f32_16x16x32_bf16 v[28:31], v[220:223], v[188:191], v[28:31]
	v_mfma_f32_16x16x32_bf16 v[24:27], v[228:231], v[188:191], v[24:27]
	v_mfma_f32_16x16x32_bf16 v[20:23], v[220:223], v[196:199], v[20:23]
	v_mfma_f32_16x16x32_bf16 v[16:19], v[228:231], v[196:199], v[16:19]
	v_mfma_f32_16x16x32_bf16 v[12:15], v[220:223], v[204:207], v[12:15]
	v_mfma_f32_16x16x32_bf16 v[8:11], v[228:231], v[204:207], v[8:11]
	v_mfma_f32_16x16x32_bf16 v[4:7], v[220:223], v[212:215], v[4:7]
	v_mfma_f32_16x16x32_bf16 v[0:3], v[228:231], v[212:215], v[0:3]
	v_mfma_f32_16x16x32_bf16 v[28:31], v[224:227], v[192:195], v[28:31]
	v_mfma_f32_16x16x32_bf16 v[24:27], v[232:235], v[192:195], v[24:27]
	v_mfma_f32_16x16x32_bf16 v[20:23], v[224:227], v[200:203], v[20:23]
	v_mfma_f32_16x16x32_bf16 v[16:19], v[232:235], v[200:203], v[16:19]
	v_mfma_f32_16x16x32_bf16 v[12:15], v[224:227], v[208:211], v[12:15]
	v_mfma_f32_16x16x32_bf16 v[8:11], v[232:235], v[208:211], v[8:11]
	v_mfma_f32_16x16x32_bf16 v[4:7], v[224:227], v[216:219], v[4:7]
	v_mfma_f32_16x16x32_bf16 v[0:3], v[232:235], v[216:219], v[0:3]
	s_barrier
	ds_read_b128 v[172:175], v160
	ds_read_b128 v[176:179], v160 offset:1024
	ds_read_b128 v[180:183], v160 offset:2048
	ds_read_b128 v[184:187], v160 offset:3072
	v_readfirstlane_b32 s23, v159
	v_lshl_add_u64 v[220:221], v[236:237], 0, s[16:17]
	s_mov_b32 m0, s23
	v_readfirstlane_b32 s23, v161
	ds_read_b128 v[188:191], v151 offset:32768
	ds_read_b128 v[192:195], v151 offset:33792
	ds_read_b128 v[196:199], v150 offset:32768
	ds_read_b128 v[200:203], v150 offset:33792
	ds_read_b128 v[204:207], v145 offset:32768
	ds_read_b128 v[208:211], v145 offset:33792
	ds_read_b128 v[212:215], v144 offset:32768
	ds_read_b128 v[216:219], v144 offset:33792
	global_load_lds_dwordx4 v[220:221], off
	v_lshl_add_u64 v[220:221], v[238:239], 0, s[16:17]
	s_mov_b32 m0, s23
	s_nop 0
	global_load_lds_dwordx4 v[220:221], off
	s_waitcnt lgkmcnt(8)
	s_barrier
	s_waitcnt lgkmcnt(0)
	s_waitcnt lgkmcnt(0)
	v_mfma_f32_16x16x32_bf16 v[124:127], v[172:175], v[188:191], v[124:127]
	v_mfma_f32_16x16x32_bf16 v[120:123], v[180:183], v[188:191], v[120:123]
	v_mfma_f32_16x16x32_bf16 v[116:119], v[172:175], v[196:199], v[116:119]
	v_mfma_f32_16x16x32_bf16 v[112:115], v[180:183], v[196:199], v[112:115]
	v_mfma_f32_16x16x32_bf16 v[108:111], v[172:175], v[204:207], v[108:111]
	v_mfma_f32_16x16x32_bf16 v[104:107], v[180:183], v[204:207], v[104:107]
	v_mfma_f32_16x16x32_bf16 v[100:103], v[172:175], v[212:215], v[100:103]
	v_mfma_f32_16x16x32_bf16 v[96:99], v[180:183], v[212:215], v[96:99]
	v_mfma_f32_16x16x32_bf16 v[124:127], v[176:179], v[192:195], v[124:127]
	v_mfma_f32_16x16x32_bf16 v[120:123], v[184:187], v[192:195], v[120:123]
	v_mfma_f32_16x16x32_bf16 v[116:119], v[176:179], v[200:203], v[116:119]
	v_mfma_f32_16x16x32_bf16 v[112:115], v[184:187], v[200:203], v[112:115]
	v_mfma_f32_16x16x32_bf16 v[108:111], v[176:179], v[208:211], v[108:111]
	v_mfma_f32_16x16x32_bf16 v[104:107], v[184:187], v[208:211], v[104:107]
	v_mfma_f32_16x16x32_bf16 v[100:103], v[176:179], v[216:219], v[100:103]
	v_mfma_f32_16x16x32_bf16 v[96:99], v[184:187], v[216:219], v[96:99]
	s_barrier
	v_readfirstlane_b32 s23, v162
	v_lshl_add_u64 v[244:245], v[240:241], 0, s[18:19]
	s_mov_b32 m0, s23
	v_readfirstlane_b32 s23, v163
	ds_read_b128 v[220:223], v154
	ds_read_b128 v[224:227], v154 offset:1024
	ds_read_b128 v[228:231], v154 offset:2048
	ds_read_b128 v[232:235], v154 offset:3072
	global_load_lds_dwordx4 v[244:245], off
	v_lshl_add_u64 v[244:245], v[242:243], 0, s[18:19]
	s_mov_b32 m0, s23
	s_nop 0
	global_load_lds_dwordx4 v[244:245], off
	s_barrier
	s_waitcnt lgkmcnt(0)
	s_waitcnt lgkmcnt(0)
	v_mfma_f32_16x16x32_bf16 v[92:95], v[220:223], v[188:191], v[92:95]
	v_mfma_f32_16x16x32_bf16 v[88:91], v[228:231], v[188:191], v[88:91]
	v_mfma_f32_16x16x32_bf16 v[84:87], v[220:223], v[196:199], v[84:87]
	v_mfma_f32_16x16x32_bf16 v[80:83], v[228:231], v[196:199], v[80:83]
	v_mfma_f32_16x16x32_bf16 v[76:79], v[220:223], v[204:207], v[76:79]
	v_mfma_f32_16x16x32_bf16 v[72:75], v[228:231], v[204:207], v[72:75]
	v_mfma_f32_16x16x32_bf16 v[68:71], v[220:223], v[212:215], v[68:71]
	v_mfma_f32_16x16x32_bf16 v[64:67], v[228:231], v[212:215], v[64:67]
	v_mfma_f32_16x16x32_bf16 v[92:95], v[224:227], v[192:195], v[92:95]
	v_mfma_f32_16x16x32_bf16 v[88:91], v[232:235], v[192:195], v[88:91]
	v_mfma_f32_16x16x32_bf16 v[84:87], v[224:227], v[200:203], v[84:87]
	v_mfma_f32_16x16x32_bf16 v[80:83], v[232:235], v[200:203], v[80:83]
	v_mfma_f32_16x16x32_bf16 v[76:79], v[224:227], v[208:211], v[76:79]
	v_mfma_f32_16x16x32_bf16 v[72:75], v[232:235], v[208:211], v[72:75]
	v_mfma_f32_16x16x32_bf16 v[68:71], v[224:227], v[216:219], v[68:71]
	v_mfma_f32_16x16x32_bf16 v[64:67], v[232:235], v[216:219], v[64:67]
	v_readfirstlane_b32 s23, v164
	v_lshl_add_u64 v[236:237], v[236:237], 0, s[18:19]
	s_mov_b32 m0, s23
	v_readfirstlane_b32 s23, v165
	s_barrier
	ds_read_b128 v[188:191], v151 offset:49152
	ds_read_b128 v[192:195], v151 offset:50176
	ds_read_b128 v[196:199], v150 offset:49152
	ds_read_b128 v[200:203], v150 offset:50176
	ds_read_b128 v[204:207], v145 offset:49152
	ds_read_b128 v[208:211], v145 offset:50176
	ds_read_b128 v[212:215], v144 offset:49152
	ds_read_b128 v[216:219], v144 offset:50176
	global_load_lds_dwordx4 v[236:237], off
	v_lshl_add_u64 v[236:237], v[238:239], 0, s[18:19]
	s_mov_b32 m0, s23
	s_nop 0
	global_load_lds_dwordx4 v[236:237], off
	s_barrier
; #define WAIT_V(n) asm volatile("s_waitcnt vmcnt(" #n ")" ::: "memory")
; #define WAIT_L(n) asm volatile("s_waitcnt lgkmcnt(" #n ")" ::: "memory")
; #define BAR __builtin_amdgcn_s_barrier()
; #define SCHED __builtin_amdgcn_sched_barrier(0)
;     ...
;     BAR; WAIT_L(0); MMA(1, 0, At, B0); BAR; SCHED;
;     STAGE(SB(1, 1), Bt, bcol1, t + 3);
;     WAIT_V(6); BAR; MMA(1, 1, At, B1); BAR;
;   }
;   { LDB(B0, 0, 0); LDA(At, 0, 0); STAGE(SA(1, 1), A, brow + HALF, nt - 1);
;     BAR; WAIT_L(0); MMA(0, 0, At, B0); BAR;
;     LDB(B1, 0, 1); BAR; WAIT_L(0); MMA(0, 1, At, B1); BAR;
	s_waitcnt lgkmcnt(0)
	s_waitcnt lgkmcnt(0)
	v_mfma_f32_16x16x32_bf16 v[60:63], v[172:175], v[188:191], v[60:63]
	v_mfma_f32_16x16x32_bf16 v[56:59], v[180:183], v[188:191], v[56:59]
	v_mfma_f32_16x16x32_bf16 v[52:55], v[172:175], v[196:199], v[52:55]
	v_mfma_f32_16x16x32_bf16 v[48:51], v[180:183], v[196:199], v[48:51]
	v_mfma_f32_16x16x32_bf16 v[44:47], v[172:175], v[204:207], v[44:47]
	v_mfma_f32_16x16x32_bf16 v[40:43], v[180:183], v[204:207], v[40:43]
	v_mfma_f32_16x16x32_bf16 v[36:39], v[172:175], v[212:215], v[36:39]
	v_mfma_f32_16x16x32_bf16 v[32:35], v[180:183], v[212:215], v[32:35]
	v_mfma_f32_16x16x32_bf16 v[60:63], v[176:179], v[192:195], v[60:63]
	v_mfma_f32_16x16x32_bf16 v[56:59], v[184:187], v[192:195], v[56:59]
	v_mfma_f32_16x16x32_bf16 v[52:55], v[176:179], v[200:203], v[52:55]
	v_mfma_f32_16x16x32_bf16 v[48:51], v[184:187], v[200:203], v[48:51]
	v_mfma_f32_16x16x32_bf16 v[44:47], v[176:179], v[208:211], v[44:47]
	v_mfma_f32_16x16x32_bf16 v[40:43], v[184:187], v[208:211], v[40:43]
	v_mfma_f32_16x16x32_bf16 v[36:39], v[176:179], v[216:219], v[36:39]
	v_mfma_f32_16x16x32_bf16 v[32:35], v[184:187], v[216:219], v[32:35]
	s_barrier
	v_readfirstlane_b32 s23, v166
	v_lshl_add_u64 v[172:173], v[240:241], 0, s[20:21]
	s_mov_b32 m0, s23
	v_readfirstlane_b32 s23, v167
	global_load_lds_dwordx4 v[172:173], off
	v_lshl_add_u64 v[172:173], v[242:243], 0, s[20:21]
	s_mov_b32 m0, s23
	s_nop 0
	global_load_lds_dwordx4 v[172:173], off
	s_waitcnt vmcnt(6)
	s_barrier
	v_mfma_f32_16x16x32_bf16 v[28:31], v[220:223], v[188:191], v[28:31]
	v_mfma_f32_16x16x32_bf16 v[24:27], v[228:231], v[188:191], v[24:27]
	v_mfma_f32_16x16x32_bf16 v[20:23], v[220:223], v[196:199], v[20:23]
	v_mfma_f32_16x16x32_bf16 v[16:19], v[228:231], v[196:199], v[16:19]
	v_mfma_f32_16x16x32_bf16 v[12:15], v[220:223], v[204:207], v[12:15]
	v_mfma_f32_16x16x32_bf16 v[8:11], v[228:231], v[204:207], v[8:11]
	v_mfma_f32_16x16x32_bf16 v[4:7], v[220:223], v[212:215], v[4:7]
	v_mfma_f32_16x16x32_bf16 v[0:3], v[228:231], v[212:215], v[0:3]
	v_mfma_f32_16x16x32_bf16 v[28:31], v[224:227], v[192:195], v[28:31]
	v_mfma_f32_16x16x32_bf16 v[24:27], v[232:235], v[192:195], v[24:27]
	v_mfma_f32_16x16x32_bf16 v[20:23], v[224:227], v[200:203], v[20:23]
	v_mfma_f32_16x16x32_bf16 v[16:19], v[232:235], v[200:203], v[16:19]
	v_mfma_f32_16x16x32_bf16 v[12:15], v[224:227], v[208:211], v[12:15]
	v_mfma_f32_16x16x32_bf16 v[8:11], v[232:235], v[208:211], v[8:11]
	v_mfma_f32_16x16x32_bf16 v[4:7], v[224:227], v[216:219], v[4:7]
	v_mfma_f32_16x16x32_bf16 v[0:3], v[232:235], v[216:219], v[0:3]
	s_add_i32 s22, s22, 2
	s_add_u32 s6, s6, 0x100
	s_addc_u32 s7, s7, 0
	s_cmpk_lt_u32 s22, 0xa8
	s_barrier
	s_cbranch_scc1 .LBB0_1335
	s_add_u32 s4, s4, 0x5580
	s_addc_u32 s5, s5, 0
	v_readfirstlane_b32 s6, v170
	v_lshl_add_u64 v[152:153], s[4:5], 0, v[128:129]
	s_mov_b32 m0, s6
	v_lshl_add_u64 v[130:131], s[4:5], 0, v[130:131]
	v_readfirstlane_b32 s4, v171
	ds_read_b128 v[132:135], v169
	ds_read_b128 v[136:139], v169 offset:1024
	ds_read_b128 v[156:159], v169 offset:2048
	ds_read_b128 v[162:165], v169 offset:3072
	ds_read_b128 v[172:175], v151
	ds_read_b128 v[176:179], v151 offset:1024
	ds_read_b128 v[180:183], v150
	ds_read_b128 v[184:187], v150 offset:1024
	ds_read_b128 v[188:191], v145
	ds_read_b128 v[192:195], v145 offset:1024
	ds_read_b128 v[196:199], v144
	ds_read_b128 v[200:203], v144 offset:1024
	global_load_lds_dwordx4 v[152:153], off
	s_mov_b32 m0, s4
	s_nop 0
	global_load_lds_dwordx4 v[130:131], off
	s_barrier
	s_waitcnt lgkmcnt(0)
	s_waitcnt lgkmcnt(0)
	v_mfma_f32_16x16x32_bf16 v[124:127], v[132:135], v[172:175], v[124:127]
	v_mfma_f32_16x16x32_bf16 v[120:123], v[156:159], v[172:175], v[120:123]
	v_mfma_f32_16x16x32_bf16 v[108:111], v[132:135], v[188:191], v[108:111]
	v_mfma_f32_16x16x32_bf16 v[104:107], v[156:159], v[188:191], v[104:107]
	v_mfma_f32_16x16x32_bf16 v[124:127], v[136:139], v[176:179], v[124:127]
	v_mfma_f32_16x16x32_bf16 v[120:123], v[162:165], v[176:179], v[120:123]
	v_mfma_f32_16x16x32_bf16 v[116:119], v[132:135], v[180:183], v[116:119]
	v_mfma_f32_16x16x32_bf16 v[112:115], v[156:159], v[180:183], v[112:115]
	v_mfma_f32_16x16x32_bf16 v[108:111], v[136:139], v[192:195], v[108:111]
	v_mfma_f32_16x16x32_bf16 v[104:107], v[162:165], v[192:195], v[104:107]
	v_mfma_f32_16x16x32_bf16 v[100:103], v[132:135], v[196:199], v[100:103]
	v_mfma_f32_16x16x32_bf16 v[96:99], v[156:159], v[196:199], v[96:99]
	v_mfma_f32_16x16x32_bf16 v[204:207], v[136:139], v[184:187], v[116:119]
	v_mfma_f32_16x16x32_bf16 v[208:211], v[162:165], v[184:187], v[112:115]
	v_mfma_f32_16x16x32_bf16 v[212:215], v[136:139], v[200:203], v[100:103]
	v_mfma_f32_16x16x32_bf16 v[216:219], v[162:165], v[200:203], v[96:99]
	s_barrier
	s_nop 1
	ds_read_b128 v[96:99], v168
	ds_read_b128 v[100:103], v168 offset:1024
	ds_read_b128 v[112:115], v168 offset:2048
	ds_read_b128 v[116:119], v168 offset:3072
	s_barrier
	s_waitcnt lgkmcnt(0)
	s_waitcnt lgkmcnt(0)
	v_mfma_f32_16x16x32_bf16 v[92:95], v[96:99], v[172:175], v[92:95]
	v_mfma_f32_16x16x32_bf16 v[88:91], v[112:115], v[172:175], v[88:91]
	v_mfma_f32_16x16x32_bf16 v[76:79], v[96:99], v[188:191], v[76:79]
	v_mfma_f32_16x16x32_bf16 v[72:75], v[112:115], v[188:191], v[72:75]
	v_mfma_f32_16x16x32_bf16 v[92:95], v[100:103], v[176:179], v[92:95]
	v_mfma_f32_16x16x32_bf16 v[88:91], v[116:119], v[176:179], v[88:91]
	v_mfma_f32_16x16x32_bf16 v[84:87], v[96:99], v[180:183], v[84:87]
	v_mfma_f32_16x16x32_bf16 v[80:83], v[112:115], v[180:183], v[80:83]
	v_mfma_f32_16x16x32_bf16 v[76:79], v[100:103], v[192:195], v[76:79]
	v_mfma_f32_16x16x32_bf16 v[72:75], v[116:119], v[192:195], v[72:75]
	v_mfma_f32_16x16x32_bf16 v[68:71], v[96:99], v[196:199], v[68:71]
	v_mfma_f32_16x16x32_bf16 v[64:67], v[112:115], v[196:199], v[64:67]
	v_mfma_f32_16x16x32_bf16 v[166:169], v[100:103], v[184:187], v[84:87]
	v_mfma_f32_16x16x32_bf16 v[170:173], v[116:119], v[184:187], v[80:83]
	v_mfma_f32_16x16x32_bf16 v[174:177], v[100:103], v[200:203], v[68:71]
	v_mfma_f32_16x16x32_bf16 v[178:181], v[116:119], v[200:203], v[64:67]
	s_barrier
; #define WAIT_V(n) asm volatile("s_waitcnt vmcnt(" #n ")" ::: "memory")
; #define WAIT_L(n) asm volatile("s_waitcnt lgkmcnt(" #n ")" ::: "memory")
; #define BAR __builtin_amdgcn_s_barrier()
;     ...
;     LDA(At, 0, 1); WAIT_V(4); BAR; WAIT_L(0); MMA(1, 0, At, B0); MMA(1, 1, At, B1); BAR; }
;   { LDB(B0, 1, 0); LDA(At, 1, 0); WAIT_V(2); BAR; WAIT_L(0); MMA(0, 0, At, B0); BAR;
	s_nop 1
	ds_read_b128 v[64:67], v151 offset:16384
	ds_read_b128 v[68:71], v151 offset:17408
	ds_read_b128 v[80:83], v150 offset:16384
	ds_read_b128 v[84:87], v150 offset:17408
	ds_read_b128 v[182:185], v145 offset:16384
	ds_read_b128 v[186:189], v145 offset:17408
	ds_read_b128 v[190:193], v144 offset:16384
	ds_read_b128 v[194:197], v144 offset:17408
	s_waitcnt vmcnt(4)
	s_barrier
	s_waitcnt lgkmcnt(0)
	s_waitcnt lgkmcnt(0)
	v_mfma_f32_16x16x32_bf16 v[60:63], v[132:135], v[64:67], v[60:63]
	v_mfma_f32_16x16x32_bf16 v[56:59], v[156:159], v[64:67], v[56:59]
	v_mfma_f32_16x16x32_bf16 v[44:47], v[132:135], v[182:185], v[44:47]
	v_mfma_f32_16x16x32_bf16 v[40:43], v[156:159], v[182:185], v[40:43]
	v_mfma_f32_16x16x32_bf16 v[60:63], v[136:139], v[68:71], v[60:63]
	v_mfma_f32_16x16x32_bf16 v[56:59], v[162:165], v[68:71], v[56:59]
	v_mfma_f32_16x16x32_bf16 v[52:55], v[132:135], v[80:83], v[52:55]
	v_mfma_f32_16x16x32_bf16 v[48:51], v[156:159], v[80:83], v[48:51]
	v_mfma_f32_16x16x32_bf16 v[44:47], v[136:139], v[186:189], v[44:47]
	v_mfma_f32_16x16x32_bf16 v[40:43], v[162:165], v[186:189], v[40:43]
	v_mfma_f32_16x16x32_bf16 v[36:39], v[132:135], v[190:193], v[36:39]
	v_mfma_f32_16x16x32_bf16 v[32:35], v[156:159], v[190:193], v[32:35]
	v_mfma_f32_16x16x32_bf16 v[198:201], v[136:139], v[84:87], v[52:55]
	v_mfma_f32_16x16x32_bf16 v[220:223], v[162:165], v[84:87], v[48:51]
	v_mfma_f32_16x16x32_bf16 v[130:133], v[136:139], v[194:197], v[36:39]
	v_mfma_f32_16x16x32_bf16 v[134:137], v[162:165], v[194:197], v[32:35]
	v_mfma_f32_16x16x32_bf16 v[28:31], v[96:99], v[64:67], v[28:31]
	v_mfma_f32_16x16x32_bf16 v[24:27], v[112:115], v[64:67], v[24:27]
	v_mfma_f32_16x16x32_bf16 v[12:15], v[96:99], v[182:185], v[12:15]
	v_mfma_f32_16x16x32_bf16 v[8:11], v[112:115], v[182:185], v[8:11]
	v_mfma_f32_16x16x32_bf16 v[28:31], v[100:103], v[68:71], v[28:31]
	v_mfma_f32_16x16x32_bf16 v[24:27], v[116:119], v[68:71], v[24:27]
	v_mfma_f32_16x16x32_bf16 v[20:23], v[96:99], v[80:83], v[20:23]
	v_mfma_f32_16x16x32_bf16 v[16:19], v[112:115], v[80:83], v[16:19]
	v_mfma_f32_16x16x32_bf16 v[12:15], v[100:103], v[186:189], v[12:15]
	v_mfma_f32_16x16x32_bf16 v[8:11], v[116:119], v[186:189], v[8:11]
	v_mfma_f32_16x16x32_bf16 v[4:7], v[96:99], v[190:193], v[4:7]
	v_mfma_f32_16x16x32_bf16 v[0:3], v[112:115], v[190:193], v[0:3]
	v_mfma_f32_16x16x32_bf16 v[156:159], v[100:103], v[84:87], v[20:23]
	v_mfma_f32_16x16x32_bf16 v[162:165], v[116:119], v[84:87], v[16:19]
	v_mfma_f32_16x16x32_bf16 v[182:185], v[100:103], v[194:197], v[4:7]
	v_mfma_f32_16x16x32_bf16 v[186:189], v[116:119], v[194:197], v[0:3]
	s_barrier
	s_nop 1
	ds_read_b128 v[0:3], v160
	ds_read_b128 v[4:7], v160 offset:1024
	ds_read_b128 v[190:193], v160 offset:2048
	ds_read_b128 v[194:197], v160 offset:3072
	ds_read_b128 v[16:19], v151 offset:32768
	ds_read_b128 v[20:23], v151 offset:33792
	ds_read_b128 v[32:35], v150 offset:32768
	ds_read_b128 v[36:39], v150 offset:33792
	ds_read_b128 v[48:51], v145 offset:32768
	ds_read_b128 v[52:55], v145 offset:33792
	ds_read_b128 v[224:227], v144 offset:32768
	ds_read_b128 v[228:231], v144 offset:33792
	s_waitcnt vmcnt(2)
	s_barrier
	s_waitcnt lgkmcnt(0)
	s_waitcnt lgkmcnt(0)
	v_mfma_f32_16x16x32_bf16 v[64:67], v[0:3], v[16:19], v[124:127]
	v_mfma_f32_16x16x32_bf16 v[112:115], v[4:7], v[20:23], v[64:67]
	v_mfma_f32_16x16x32_bf16 v[64:67], v[190:193], v[16:19], v[120:123]
	v_mfma_f32_16x16x32_bf16 v[116:119], v[194:197], v[20:23], v[64:67]
	v_mfma_f32_16x16x32_bf16 v[64:67], v[0:3], v[32:35], v[204:207]
	v_mfma_f32_16x16x32_bf16 v[96:99], v[4:7], v[36:39], v[64:67]
	v_mfma_f32_16x16x32_bf16 v[64:67], v[190:193], v[32:35], v[208:211]
	v_mfma_f32_16x16x32_bf16 v[100:103], v[194:197], v[36:39], v[64:67]
	v_mfma_f32_16x16x32_bf16 v[64:67], v[0:3], v[48:51], v[108:111]
	v_mfma_f32_16x16x32_bf16 v[80:83], v[4:7], v[52:55], v[64:67]
	v_mfma_f32_16x16x32_bf16 v[64:67], v[190:193], v[48:51], v[104:107]
	v_mfma_f32_16x16x32_bf16 v[84:87], v[194:197], v[52:55], v[64:67]
	v_mfma_f32_16x16x32_bf16 v[64:67], v[0:3], v[224:227], v[212:215]
	v_mfma_f32_16x16x32_bf16 v[68:71], v[190:193], v[224:227], v[216:219]
	v_mfma_f32_16x16x32_bf16 v[64:67], v[4:7], v[228:231], v[64:67]
	v_mfma_f32_16x16x32_bf16 v[68:71], v[194:197], v[228:231], v[68:71]
	s_barrier
; #define WAIT_V(n) asm volatile("s_waitcnt vmcnt(" #n ")" ::: "memory")
; #define WAIT_L(n) asm volatile("s_waitcnt lgkmcnt(" #n ")" ::: "memory")
; #define BAR __builtin_amdgcn_s_barrier()
;     ...
;     LDB(B1, 1, 1); WAIT_V(0); BAR; WAIT_L(0); MMA(0, 1, At, B1); BAR;
;     LDA(At, 1, 1); BAR; WAIT_L(0); MMA(1, 0, At, B0); MMA(1, 1, At, B1); BAR; }
;   if (wr == 0) BAR;
	ds_read_b128 v[202:205], v154
	ds_read_b128 v[206:209], v154 offset:1024
	ds_read_b128 v[210:213], v154 offset:2048
	ds_read_b128 v[152:155], v154 offset:3072
	s_waitcnt vmcnt(0)
	s_barrier
	s_waitcnt lgkmcnt(0)
	s_waitcnt lgkmcnt(0)
	v_mfma_f32_16x16x32_bf16 v[92:95], v[202:205], v[16:19], v[92:95]
	v_mfma_f32_16x16x32_bf16 v[16:19], v[210:213], v[16:19], v[88:91]
	v_mfma_f32_16x16x32_bf16 v[120:123], v[152:155], v[20:23], v[16:19]
	v_mfma_f32_16x16x32_bf16 v[16:19], v[202:205], v[32:35], v[166:169]
	v_mfma_f32_16x16x32_bf16 v[108:111], v[206:209], v[36:39], v[16:19]
	v_mfma_f32_16x16x32_bf16 v[16:19], v[210:213], v[32:35], v[170:173]
	v_mfma_f32_16x16x32_bf16 v[104:107], v[152:155], v[36:39], v[16:19]
	v_mfma_f32_16x16x32_bf16 v[16:19], v[202:205], v[48:51], v[76:79]
	v_mfma_f32_16x16x32_bf16 v[124:127], v[206:209], v[20:23], v[92:95]
	v_mfma_f32_16x16x32_bf16 v[92:95], v[206:209], v[52:55], v[16:19]
	v_mfma_f32_16x16x32_bf16 v[16:19], v[210:213], v[48:51], v[72:75]
	v_mfma_f32_16x16x32_bf16 v[88:91], v[152:155], v[52:55], v[16:19]
	v_mfma_f32_16x16x32_bf16 v[16:19], v[202:205], v[224:227], v[174:177]
	v_mfma_f32_16x16x32_bf16 v[76:79], v[206:209], v[228:231], v[16:19]
	v_mfma_f32_16x16x32_bf16 v[16:19], v[210:213], v[224:227], v[178:181]
	v_mfma_f32_16x16x32_bf16 v[72:75], v[152:155], v[228:231], v[16:19]
	s_barrier
	ds_read_b128 v[166:169], v151 offset:49152
	ds_read_b128 v[170:173], v151 offset:50176
	ds_read_b128 v[174:177], v150 offset:49152
	ds_read_b128 v[178:181], v150 offset:50176
	ds_read_b128 v[214:217], v145 offset:49152
	ds_read_b128 v[224:227], v145 offset:50176
	ds_read_b128 v[228:231], v144 offset:49152
	ds_read_b128 v[232:235], v144 offset:50176
	s_barrier
	s_waitcnt lgkmcnt(0)
	s_waitcnt lgkmcnt(0)
	v_mfma_f32_16x16x32_bf16 v[16:19], v[0:3], v[166:169], v[60:63]
	v_mfma_f32_16x16x32_bf16 v[48:51], v[4:7], v[170:173], v[16:19]
	v_mfma_f32_16x16x32_bf16 v[16:19], v[190:193], v[166:169], v[56:59]
	v_mfma_f32_16x16x32_bf16 v[52:55], v[194:197], v[170:173], v[16:19]
	v_mfma_f32_16x16x32_bf16 v[16:19], v[0:3], v[174:177], v[198:201]
	v_mfma_f32_16x16x32_bf16 v[32:35], v[4:7], v[178:181], v[16:19]
	v_mfma_f32_16x16x32_bf16 v[16:19], v[190:193], v[174:177], v[220:223]
	v_mfma_f32_16x16x32_bf16 v[36:39], v[194:197], v[178:181], v[16:19]
	v_mfma_f32_16x16x32_bf16 v[16:19], v[0:3], v[214:217], v[44:47]
	v_mfma_f32_16x16x32_bf16 v[0:3], v[0:3], v[228:231], v[130:133]
	v_mfma_f32_16x16x32_bf16 v[16:19], v[4:7], v[224:227], v[16:19]
	v_mfma_f32_16x16x32_bf16 v[20:23], v[190:193], v[214:217], v[40:43]
	v_mfma_f32_16x16x32_bf16 v[0:3], v[4:7], v[232:235], v[0:3]
	v_mfma_f32_16x16x32_bf16 v[4:7], v[190:193], v[228:231], v[134:137]
	v_mfma_f32_16x16x32_bf16 v[20:23], v[194:197], v[224:227], v[20:23]
	v_mfma_f32_16x16x32_bf16 v[4:7], v[194:197], v[232:235], v[4:7]
	v_mfma_f32_16x16x32_bf16 v[24:27], v[210:213], v[166:169], v[24:27]
	v_mfma_f32_16x16x32_bf16 v[56:59], v[152:155], v[170:173], v[24:27]
	v_mfma_f32_16x16x32_bf16 v[24:27], v[202:205], v[174:177], v[156:159]
	v_mfma_f32_16x16x32_bf16 v[44:47], v[206:209], v[178:181], v[24:27]
	v_mfma_f32_16x16x32_bf16 v[24:27], v[210:213], v[174:177], v[162:165]
	v_mfma_f32_16x16x32_bf16 v[8:11], v[210:213], v[214:217], v[8:11]
	v_mfma_f32_16x16x32_bf16 v[28:31], v[202:205], v[166:169], v[28:31]
	v_mfma_f32_16x16x32_bf16 v[40:43], v[152:155], v[178:181], v[24:27]
	v_mfma_f32_16x16x32_bf16 v[12:15], v[202:205], v[214:217], v[12:15]
	v_mfma_f32_16x16x32_bf16 v[24:27], v[152:155], v[224:227], v[8:11]
	v_mfma_f32_16x16x32_bf16 v[8:11], v[202:205], v[228:231], v[182:185]
	v_mfma_f32_16x16x32_bf16 v[60:63], v[206:209], v[170:173], v[28:31]
	v_mfma_f32_16x16x32_bf16 v[28:31], v[206:209], v[224:227], v[12:15]
	v_mfma_f32_16x16x32_bf16 v[12:15], v[206:209], v[232:235], v[8:11]
	v_mfma_f32_16x16x32_bf16 v[8:11], v[210:213], v[228:231], v[186:189]
	v_mfma_f32_16x16x32_bf16 v[8:11], v[152:155], v[232:235], v[8:11]
	v_cmp_gt_u32_e32 vcc, s30, v148
	s_barrier
	s_and_saveexec_b64 s[4:5], vcc
	s_cbranch_execz .LBB0_1338
	s_barrier
